# n2 QK^T K-fragment prefetch ring, xpose tile loop waits moved to consumers, n3 finalize operand loads batched per m-tile
# speedup vs baseline: 1.0501x; 1.0038x over previous
.LBB0_58:
	s_mov_b32 s47, 1
	s_mov_b64 s[14:15], -1
	s_mov_b64 s[16:17], 0
	s_and_b64 vcc, exec, s[12:13]
	s_cbranch_vccnz .LBB0_56

.LBB0_76:
	s_xor_b64 s[12:13], s[16:17], -1
	s_add_i32 s14, s47, 1
	s_lshl_b32 s76, s14, 4
	v_lshl_add_u64 v[2:3], s[76:77], 2, v[106:107]
	v_lshl_add_u64 v[68:69], v[2:3], 0, v[122:123]
	global_load_dword v250, v[68:69], off
	s_lshl_b32 s76, s14, 12
	v_lshl_add_u64 v[68:69], v[124:125], 0, s[76:77]
	global_load_dwordx2 v[76:77], v[68:69], off
	global_load_dwordx2 v[78:79], v[68:69], off offset:32
	global_load_dwordx2 v[80:81], v[68:69], off offset:64
	global_load_dwordx2 v[82:83], v[68:69], off offset:96
	global_load_dwordx2 v[84:85], v[68:69], off offset:128
	global_load_dwordx2 v[86:87], v[68:69], off offset:160
	global_load_dwordx2 v[88:89], v[68:69], off offset:192
	global_load_dwordx2 v[90:91], v[68:69], off offset:224
	s_and_b64 vcc, exec, s[12:13]
	s_cbranch_vccz .Lmy_fin_m0_nl
	global_load_dwordx2 v[218:219], v[124:125], off
	global_load_dwordx2 v[220:221], v[124:125], off offset:32
	global_load_dwordx2 v[222:223], v[124:125], off offset:64
	global_load_dwordx2 v[224:225], v[124:125], off offset:96
	global_load_dwordx2 v[226:227], v[124:125], off offset:128
	global_load_dwordx2 v[228:229], v[124:125], off offset:160
	global_load_dwordx2 v[230:231], v[124:125], off offset:192
	global_load_dwordx2 v[232:233], v[124:125], off offset:224
	global_load_dwordx2 v[234:235], v[126:127], off
	global_load_dwordx2 v[236:237], v[126:127], off offset:32
	global_load_dwordx2 v[238:239], v[126:127], off offset:64
	global_load_dwordx2 v[240:241], v[126:127], off offset:96
	global_load_dwordx2 v[242:243], v[126:127], off offset:128
	global_load_dwordx2 v[244:245], v[126:127], off offset:160
	global_load_dwordx2 v[246:247], v[126:127], off offset:192
	global_load_dwordx2 v[248:249], v[126:127], off offset:224
.Lmy_fin_m0_nl:
	ds_bpermute_b32 v0, v161, v213
	s_waitcnt lgkmcnt(0)
	v_add_f32_e32 v0, v213, v0
	ds_bpermute_b32 v92, v162, v0
	s_waitcnt lgkmcnt(0)
	v_add_f32_e32 v0, v0, v92
	v_div_scale_f32 v92, s[16:17], v0, v0, 1.0
	v_rcp_f32_e32 v93, v92
	v_cmp_lt_f32_e64 s[0:1], 0, v0
	v_fma_f32 v94, -v92, v93, 1.0
	v_fmac_f32_e32 v93, v94, v93
	v_div_scale_f32 v94, vcc, 1.0, v0, 1.0
	v_mul_f32_e32 v95, v94, v93
	v_fma_f32 v96, -v92, v95, v94
	v_fmac_f32_e32 v95, v96, v93
	v_fma_f32 v92, -v92, v95, v94
	v_div_fmas_f32 v92, v92, v93, v95
	v_div_fixup_f32 v0, v92, v0, 1.0
	s_nop 0
	v_cndmask_b32_e64 v0, 0, v0, s[0:1]
	s_and_b64 vcc, exec, s[12:13]
	s_cbranch_vccnz .Lmy_fin_m0_mode1
	s_waitcnt vmcnt(8)
	v_mul_f32_e32 v0, v250, v0
	s_waitcnt vmcnt(7)
	v_mul_f32_e32 v68, v64, v0
	v_lshlrev_b32_e32 v69, 16, v76
	v_mul_f32_e32 v70, v68, v69
	v_mul_f32_e32 v68, v65, v0
	v_and_b32_e32 v69, 0xffff0000, v76
	v_mul_f32_e32 v71, v68, v69
	v_mul_f32_e32 v68, v66, v0
	v_lshlrev_b32_e32 v69, 16, v77
	v_mul_f32_e32 v72, v68, v69
	v_mul_f32_e32 v68, v67, v0
	v_and_b32_e32 v69, 0xffff0000, v77
	v_mul_f32_e32 v73, v68, v69
	v_cvt_pk_bf16_f32 v98, v70, v71
	v_cvt_pk_bf16_f32 v99, v72, v73
	global_store_dwordx2 v[126:127], v[98:99], off
	s_waitcnt vmcnt(7)
	v_mul_f32_e32 v68, v60, v0
	v_lshlrev_b32_e32 v69, 16, v78
	v_mul_f32_e32 v70, v68, v69
	v_mul_f32_e32 v68, v61, v0
	v_and_b32_e32 v69, 0xffff0000, v78
	v_mul_f32_e32 v71, v68, v69
	v_mul_f32_e32 v68, v62, v0
	v_lshlrev_b32_e32 v69, 16, v79
	v_mul_f32_e32 v72, v68, v69
	v_mul_f32_e32 v68, v63, v0
	v_and_b32_e32 v69, 0xffff0000, v79
	v_mul_f32_e32 v73, v68, v69
	v_cvt_pk_bf16_f32 v98, v70, v71
	v_cvt_pk_bf16_f32 v99, v72, v73
	global_store_dwordx2 v[126:127], v[98:99], off offset:32
	s_waitcnt vmcnt(7)
	v_mul_f32_e32 v68, v56, v0
	v_lshlrev_b32_e32 v69, 16, v80
	v_mul_f32_e32 v70, v68, v69
	v_mul_f32_e32 v68, v57, v0
	v_and_b32_e32 v69, 0xffff0000, v80
	v_mul_f32_e32 v71, v68, v69
	v_mul_f32_e32 v68, v58, v0
	v_lshlrev_b32_e32 v69, 16, v81
	v_mul_f32_e32 v72, v68, v69
	v_mul_f32_e32 v68, v59, v0
	v_and_b32_e32 v69, 0xffff0000, v81
	v_mul_f32_e32 v73, v68, v69
	v_cvt_pk_bf16_f32 v98, v70, v71
	v_cvt_pk_bf16_f32 v99, v72, v73
	global_store_dwordx2 v[126:127], v[98:99], off offset:64
	s_waitcnt vmcnt(7)
	v_mul_f32_e32 v68, v52, v0
	v_lshlrev_b32_e32 v69, 16, v82
	v_mul_f32_e32 v70, v68, v69
	v_mul_f32_e32 v68, v53, v0
	v_and_b32_e32 v69, 0xffff0000, v82
	v_mul_f32_e32 v71, v68, v69
	v_mul_f32_e32 v68, v54, v0
	v_lshlrev_b32_e32 v69, 16, v83
	v_mul_f32_e32 v72, v68, v69
	v_mul_f32_e32 v68, v55, v0
	v_and_b32_e32 v69, 0xffff0000, v83
	v_mul_f32_e32 v73, v68, v69
	v_cvt_pk_bf16_f32 v98, v70, v71
	v_cvt_pk_bf16_f32 v99, v72, v73
	global_store_dwordx2 v[126:127], v[98:99], off offset:96
	s_waitcnt vmcnt(7)
	v_mul_f32_e32 v68, v48, v0
	v_lshlrev_b32_e32 v69, 16, v84
	v_mul_f32_e32 v70, v68, v69
	v_mul_f32_e32 v68, v49, v0
	v_and_b32_e32 v69, 0xffff0000, v84
	v_mul_f32_e32 v71, v68, v69
	v_mul_f32_e32 v68, v50, v0
	v_lshlrev_b32_e32 v69, 16, v85
	v_mul_f32_e32 v72, v68, v69
	v_mul_f32_e32 v68, v51, v0
	v_and_b32_e32 v69, 0xffff0000, v85
	v_mul_f32_e32 v73, v68, v69
	v_cvt_pk_bf16_f32 v98, v70, v71
	v_cvt_pk_bf16_f32 v99, v72, v73
	global_store_dwordx2 v[126:127], v[98:99], off offset:128
	s_waitcnt vmcnt(7)
	v_mul_f32_e32 v68, v44, v0
	v_lshlrev_b32_e32 v69, 16, v86
	v_mul_f32_e32 v70, v68, v69
	v_mul_f32_e32 v68, v45, v0
	v_and_b32_e32 v69, 0xffff0000, v86
	v_mul_f32_e32 v71, v68, v69
	v_mul_f32_e32 v68, v46, v0
	v_lshlrev_b32_e32 v69, 16, v87
	v_mul_f32_e32 v72, v68, v69
	v_mul_f32_e32 v68, v47, v0
	v_and_b32_e32 v69, 0xffff0000, v87
	v_mul_f32_e32 v73, v68, v69
	v_cvt_pk_bf16_f32 v98, v70, v71
	v_cvt_pk_bf16_f32 v99, v72, v73
	global_store_dwordx2 v[126:127], v[98:99], off offset:160
	s_waitcnt vmcnt(7)
	v_mul_f32_e32 v68, v40, v0
	v_lshlrev_b32_e32 v69, 16, v88
	v_mul_f32_e32 v70, v68, v69
	v_mul_f32_e32 v68, v41, v0
	v_and_b32_e32 v69, 0xffff0000, v88
	v_mul_f32_e32 v71, v68, v69
	v_mul_f32_e32 v68, v42, v0
	v_lshlrev_b32_e32 v69, 16, v89
	v_mul_f32_e32 v72, v68, v69
	v_mul_f32_e32 v68, v43, v0
	v_and_b32_e32 v69, 0xffff0000, v89
	v_mul_f32_e32 v73, v68, v69
	v_cvt_pk_bf16_f32 v98, v70, v71
	v_cvt_pk_bf16_f32 v99, v72, v73
	global_store_dwordx2 v[126:127], v[98:99], off offset:192
	s_waitcnt vmcnt(7)
	v_mul_f32_e32 v68, v36, v0
	v_lshlrev_b32_e32 v69, 16, v90
	v_mul_f32_e32 v70, v68, v69
	v_mul_f32_e32 v68, v37, v0
	v_and_b32_e32 v69, 0xffff0000, v90
	v_mul_f32_e32 v71, v68, v69
	v_mul_f32_e32 v68, v38, v0
	v_lshlrev_b32_e32 v69, 16, v91
	v_mul_f32_e32 v72, v68, v69
	v_mul_f32_e32 v68, v39, v0
	v_and_b32_e32 v69, 0xffff0000, v91
	v_mul_f32_e32 v73, v68, v69
	v_cvt_pk_bf16_f32 v98, v70, v71
	v_cvt_pk_bf16_f32 v99, v72, v73
	global_store_dwordx2 v[126:127], v[98:99], off offset:224
	s_branch .Lmy_fin_m0_done
.Lmy_fin_m0_mode1:
	s_waitcnt vmcnt(24)
	v_mul_f32_e32 v0, v250, v0
	s_waitcnt vmcnt(7)
	v_mul_f32_e32 v68, v64, v0
	v_lshlrev_b32_e32 v69, 16, v76
	v_mul_f32_e32 v70, v68, v69
	v_mul_f32_e32 v68, v65, v0
	v_and_b32_e32 v69, 0xffff0000, v76
	v_mul_f32_e32 v71, v68, v69
	v_mul_f32_e32 v68, v66, v0
	v_lshlrev_b32_e32 v69, 16, v77
	v_mul_f32_e32 v72, v68, v69
	v_mul_f32_e32 v68, v67, v0
	v_and_b32_e32 v69, 0xffff0000, v77
	v_mul_f32_e32 v73, v68, v69
	v_lshlrev_b32_e32 v74, 16, v218
	v_lshlrev_b32_e32 v75, 16, v234
	v_and_b32_e32 v92, 0xffff0000, v234
	v_and_b32_e32 v93, 0xffff0000, v218
	v_add_f32_e32 v74, v75, v74
	v_add_f32_e32 v93, v92, v93
	v_lshlrev_b32_e32 v94, 16, v219
	v_lshlrev_b32_e32 v75, 16, v235
	v_and_b32_e32 v92, 0xffff0000, v235
	v_and_b32_e32 v95, 0xffff0000, v219
	v_add_f32_e32 v95, v92, v95
	v_add_f32_e32 v93, v71, v93
	v_add_f32_e32 v94, v75, v94
	v_add_f32_e32 v95, v73, v95
	v_add_f32_e32 v74, v70, v74
	v_add_f32_e32 v94, v72, v94
	v_cvt_pk_bf16_f32 v98, v74, v93
	v_cvt_pk_bf16_f32 v99, v94, v95
	global_store_dwordx2 v[126:127], v[98:99], off
	s_waitcnt vmcnt(7)
	v_mul_f32_e32 v68, v60, v0
	v_lshlrev_b32_e32 v69, 16, v78
	v_mul_f32_e32 v70, v68, v69
	v_mul_f32_e32 v68, v61, v0
	v_and_b32_e32 v69, 0xffff0000, v78
	v_mul_f32_e32 v71, v68, v69
	v_mul_f32_e32 v68, v62, v0
	v_lshlrev_b32_e32 v69, 16, v79
	v_mul_f32_e32 v72, v68, v69
	v_mul_f32_e32 v68, v63, v0
	v_and_b32_e32 v69, 0xffff0000, v79
	v_mul_f32_e32 v73, v68, v69
	v_lshlrev_b32_e32 v74, 16, v220
	v_lshlrev_b32_e32 v75, 16, v236
	v_and_b32_e32 v92, 0xffff0000, v236
	v_and_b32_e32 v93, 0xffff0000, v220
	v_add_f32_e32 v74, v75, v74
	v_add_f32_e32 v93, v92, v93
	v_lshlrev_b32_e32 v94, 16, v221
	v_lshlrev_b32_e32 v75, 16, v237
	v_and_b32_e32 v92, 0xffff0000, v237
	v_and_b32_e32 v95, 0xffff0000, v221
	v_add_f32_e32 v95, v92, v95
	v_add_f32_e32 v93, v71, v93
	v_add_f32_e32 v94, v75, v94
	v_add_f32_e32 v95, v73, v95
	v_add_f32_e32 v74, v70, v74
	v_add_f32_e32 v94, v72, v94
	v_cvt_pk_bf16_f32 v98, v74, v93
	v_cvt_pk_bf16_f32 v99, v94, v95
	global_store_dwordx2 v[126:127], v[98:99], off offset:32
	s_waitcnt vmcnt(7)
	v_mul_f32_e32 v68, v56, v0
	v_lshlrev_b32_e32 v69, 16, v80
	v_mul_f32_e32 v70, v68, v69
	v_mul_f32_e32 v68, v57, v0
	v_and_b32_e32 v69, 0xffff0000, v80
	v_mul_f32_e32 v71, v68, v69
	v_mul_f32_e32 v68, v58, v0
	v_lshlrev_b32_e32 v69, 16, v81
	v_mul_f32_e32 v72, v68, v69
	v_mul_f32_e32 v68, v59, v0
	v_and_b32_e32 v69, 0xffff0000, v81
	v_mul_f32_e32 v73, v68, v69
	v_lshlrev_b32_e32 v74, 16, v222
	v_lshlrev_b32_e32 v75, 16, v238
	v_and_b32_e32 v92, 0xffff0000, v238
	v_and_b32_e32 v93, 0xffff0000, v222
	v_add_f32_e32 v74, v75, v74
	v_add_f32_e32 v93, v92, v93
	v_lshlrev_b32_e32 v94, 16, v223
	v_lshlrev_b32_e32 v75, 16, v239
	v_and_b32_e32 v92, 0xffff0000, v239
	v_and_b32_e32 v95, 0xffff0000, v223
	v_add_f32_e32 v95, v92, v95
	v_add_f32_e32 v93, v71, v93
	v_add_f32_e32 v94, v75, v94
	v_add_f32_e32 v95, v73, v95
	v_add_f32_e32 v74, v70, v74
	v_add_f32_e32 v94, v72, v94
	v_cvt_pk_bf16_f32 v98, v74, v93
	v_cvt_pk_bf16_f32 v99, v94, v95
	global_store_dwordx2 v[126:127], v[98:99], off offset:64
	s_waitcnt vmcnt(7)
	v_mul_f32_e32 v68, v52, v0
	v_lshlrev_b32_e32 v69, 16, v82
	v_mul_f32_e32 v70, v68, v69
	v_mul_f32_e32 v68, v53, v0
	v_and_b32_e32 v69, 0xffff0000, v82
	v_mul_f32_e32 v71, v68, v69
	v_mul_f32_e32 v68, v54, v0
	v_lshlrev_b32_e32 v69, 16, v83
	v_mul_f32_e32 v72, v68, v69
	v_mul_f32_e32 v68, v55, v0
	v_and_b32_e32 v69, 0xffff0000, v83
	v_mul_f32_e32 v73, v68, v69
	v_lshlrev_b32_e32 v74, 16, v224
	v_lshlrev_b32_e32 v75, 16, v240
	v_and_b32_e32 v92, 0xffff0000, v240
	v_and_b32_e32 v93, 0xffff0000, v224
	v_add_f32_e32 v74, v75, v74
	v_add_f32_e32 v93, v92, v93
	v_lshlrev_b32_e32 v94, 16, v225
	v_lshlrev_b32_e32 v75, 16, v241
	v_and_b32_e32 v92, 0xffff0000, v241
	v_and_b32_e32 v95, 0xffff0000, v225
	v_add_f32_e32 v95, v92, v95
	v_add_f32_e32 v93, v71, v93
	v_add_f32_e32 v94, v75, v94
	v_add_f32_e32 v95, v73, v95
	v_add_f32_e32 v74, v70, v74
	v_add_f32_e32 v94, v72, v94
	v_cvt_pk_bf16_f32 v98, v74, v93
	v_cvt_pk_bf16_f32 v99, v94, v95
	global_store_dwordx2 v[126:127], v[98:99], off offset:96
	s_waitcnt vmcnt(7)
	v_mul_f32_e32 v68, v48, v0
	v_lshlrev_b32_e32 v69, 16, v84
	v_mul_f32_e32 v70, v68, v69
	v_mul_f32_e32 v68, v49, v0
	v_and_b32_e32 v69, 0xffff0000, v84
	v_mul_f32_e32 v71, v68, v69
	v_mul_f32_e32 v68, v50, v0
	v_lshlrev_b32_e32 v69, 16, v85
	v_mul_f32_e32 v72, v68, v69
	v_mul_f32_e32 v68, v51, v0
	v_and_b32_e32 v69, 0xffff0000, v85
	v_mul_f32_e32 v73, v68, v69
	v_lshlrev_b32_e32 v74, 16, v226
	v_lshlrev_b32_e32 v75, 16, v242
	v_and_b32_e32 v92, 0xffff0000, v242
	v_and_b32_e32 v93, 0xffff0000, v226
	v_add_f32_e32 v74, v75, v74
	v_add_f32_e32 v93, v92, v93
	v_lshlrev_b32_e32 v94, 16, v227
	v_lshlrev_b32_e32 v75, 16, v243
	v_and_b32_e32 v92, 0xffff0000, v243
	v_and_b32_e32 v95, 0xffff0000, v227
	v_add_f32_e32 v95, v92, v95
	v_add_f32_e32 v93, v71, v93
	v_add_f32_e32 v94, v75, v94
	v_add_f32_e32 v95, v73, v95
	v_add_f32_e32 v74, v70, v74
	v_add_f32_e32 v94, v72, v94
	v_cvt_pk_bf16_f32 v98, v74, v93
	v_cvt_pk_bf16_f32 v99, v94, v95
	global_store_dwordx2 v[126:127], v[98:99], off offset:128
	s_waitcnt vmcnt(7)
	v_mul_f32_e32 v68, v44, v0
	v_lshlrev_b32_e32 v69, 16, v86
	v_mul_f32_e32 v70, v68, v69
	v_mul_f32_e32 v68, v45, v0
	v_and_b32_e32 v69, 0xffff0000, v86
	v_mul_f32_e32 v71, v68, v69
	v_mul_f32_e32 v68, v46, v0
	v_lshlrev_b32_e32 v69, 16, v87
	v_mul_f32_e32 v72, v68, v69
	v_mul_f32_e32 v68, v47, v0
	v_and_b32_e32 v69, 0xffff0000, v87
	v_mul_f32_e32 v73, v68, v69
	v_lshlrev_b32_e32 v74, 16, v228
	v_lshlrev_b32_e32 v75, 16, v244
	v_and_b32_e32 v92, 0xffff0000, v244
	v_and_b32_e32 v93, 0xffff0000, v228
	v_add_f32_e32 v74, v75, v74
	v_add_f32_e32 v93, v92, v93
	v_lshlrev_b32_e32 v94, 16, v229
	v_lshlrev_b32_e32 v75, 16, v245
	v_and_b32_e32 v92, 0xffff0000, v245
	v_and_b32_e32 v95, 0xffff0000, v229
	v_add_f32_e32 v95, v92, v95
	v_add_f32_e32 v93, v71, v93
	v_add_f32_e32 v94, v75, v94
	v_add_f32_e32 v95, v73, v95
	v_add_f32_e32 v74, v70, v74
	v_add_f32_e32 v94, v72, v94
	v_cvt_pk_bf16_f32 v98, v74, v93
	v_cvt_pk_bf16_f32 v99, v94, v95
	global_store_dwordx2 v[126:127], v[98:99], off offset:160
	s_waitcnt vmcnt(7)
	v_mul_f32_e32 v68, v40, v0
	v_lshlrev_b32_e32 v69, 16, v88
	v_mul_f32_e32 v70, v68, v69
	v_mul_f32_e32 v68, v41, v0
	v_and_b32_e32 v69, 0xffff0000, v88
	v_mul_f32_e32 v71, v68, v69
	v_mul_f32_e32 v68, v42, v0
	v_lshlrev_b32_e32 v69, 16, v89
	v_mul_f32_e32 v72, v68, v69
	v_mul_f32_e32 v68, v43, v0
	v_and_b32_e32 v69, 0xffff0000, v89
	v_mul_f32_e32 v73, v68, v69
	v_lshlrev_b32_e32 v74, 16, v230
	v_lshlrev_b32_e32 v75, 16, v246
	v_and_b32_e32 v92, 0xffff0000, v246
	v_and_b32_e32 v93, 0xffff0000, v230
	v_add_f32_e32 v74, v75, v74
	v_add_f32_e32 v93, v92, v93
	v_lshlrev_b32_e32 v94, 16, v231
	v_lshlrev_b32_e32 v75, 16, v247
	v_and_b32_e32 v92, 0xffff0000, v247
	v_and_b32_e32 v95, 0xffff0000, v231
	v_add_f32_e32 v95, v92, v95
	v_add_f32_e32 v93, v71, v93
	v_add_f32_e32 v94, v75, v94
	v_add_f32_e32 v95, v73, v95
	v_add_f32_e32 v74, v70, v74
	v_add_f32_e32 v94, v72, v94
	v_cvt_pk_bf16_f32 v98, v74, v93
	v_cvt_pk_bf16_f32 v99, v94, v95
	global_store_dwordx2 v[126:127], v[98:99], off offset:192
	s_waitcnt vmcnt(7)
	v_mul_f32_e32 v68, v36, v0
	v_lshlrev_b32_e32 v69, 16, v90
	v_mul_f32_e32 v70, v68, v69
	v_mul_f32_e32 v68, v37, v0
	v_and_b32_e32 v69, 0xffff0000, v90
	v_mul_f32_e32 v71, v68, v69
	v_mul_f32_e32 v68, v38, v0
	v_lshlrev_b32_e32 v69, 16, v91
	v_mul_f32_e32 v72, v68, v69
	v_mul_f32_e32 v68, v39, v0
	v_and_b32_e32 v69, 0xffff0000, v91
	v_mul_f32_e32 v73, v68, v69
	v_lshlrev_b32_e32 v74, 16, v232
	v_lshlrev_b32_e32 v75, 16, v248
	v_and_b32_e32 v92, 0xffff0000, v248
	v_and_b32_e32 v93, 0xffff0000, v232
	v_add_f32_e32 v74, v75, v74
	v_add_f32_e32 v93, v92, v93
	v_lshlrev_b32_e32 v94, 16, v233
	v_lshlrev_b32_e32 v75, 16, v249
	v_and_b32_e32 v92, 0xffff0000, v249
	v_and_b32_e32 v95, 0xffff0000, v233
	v_add_f32_e32 v95, v92, v95
	v_add_f32_e32 v93, v71, v93
	v_add_f32_e32 v94, v75, v94
	v_add_f32_e32 v95, v73, v95
	v_add_f32_e32 v74, v70, v74
	v_add_f32_e32 v94, v72, v94
	v_cvt_pk_bf16_f32 v98, v74, v93
	v_cvt_pk_bf16_f32 v99, v94, v95
	global_store_dwordx2 v[126:127], v[98:99], off offset:224
.Lmy_fin_m0_done:
	s_lshl_b32 s76, s14, 4
	v_lshl_add_u64 v[2:3], s[76:77], 2, v[106:107]
	v_lshl_add_u64 v[68:69], v[2:3], 0, v[128:129]
	global_load_dword v250, v[68:69], off
	s_lshl_b32 s76, s14, 12
	v_lshl_add_u64 v[68:69], v[132:133], 0, s[76:77]
	global_load_dwordx2 v[76:77], v[68:69], off
	global_load_dwordx2 v[78:79], v[68:69], off offset:32
	global_load_dwordx2 v[80:81], v[68:69], off offset:64
	global_load_dwordx2 v[82:83], v[68:69], off offset:96
	global_load_dwordx2 v[84:85], v[68:69], off offset:128
	global_load_dwordx2 v[86:87], v[68:69], off offset:160
	global_load_dwordx2 v[88:89], v[68:69], off offset:192
	global_load_dwordx2 v[90:91], v[68:69], off offset:224
	s_and_b64 vcc, exec, s[12:13]
	s_cbranch_vccz .Lmy_fin_m1_nl
	global_load_dwordx2 v[218:219], v[132:133], off
	global_load_dwordx2 v[220:221], v[132:133], off offset:32
	global_load_dwordx2 v[222:223], v[132:133], off offset:64
	global_load_dwordx2 v[224:225], v[132:133], off offset:96
	global_load_dwordx2 v[226:227], v[132:133], off offset:128
	global_load_dwordx2 v[228:229], v[132:133], off offset:160
	global_load_dwordx2 v[230:231], v[132:133], off offset:192
	global_load_dwordx2 v[232:233], v[132:133], off offset:224
	global_load_dwordx2 v[234:235], v[134:135], off
	global_load_dwordx2 v[236:237], v[134:135], off offset:32
	global_load_dwordx2 v[238:239], v[134:135], off offset:64
	global_load_dwordx2 v[240:241], v[134:135], off offset:96
	global_load_dwordx2 v[242:243], v[134:135], off offset:128
	global_load_dwordx2 v[244:245], v[134:135], off offset:160
	global_load_dwordx2 v[246:247], v[134:135], off offset:192
	global_load_dwordx2 v[248:249], v[134:135], off offset:224
.Lmy_fin_m1_nl:
	ds_bpermute_b32 v0, v161, v212
	s_waitcnt lgkmcnt(0)
	v_add_f32_e32 v0, v212, v0
	ds_bpermute_b32 v92, v162, v0
	s_waitcnt lgkmcnt(0)
	v_add_f32_e32 v0, v0, v92
	v_div_scale_f32 v92, s[16:17], v0, v0, 1.0
	v_rcp_f32_e32 v93, v92
	v_cmp_lt_f32_e64 s[0:1], 0, v0
	v_fma_f32 v94, -v92, v93, 1.0
	v_fmac_f32_e32 v93, v94, v93
	v_div_scale_f32 v94, vcc, 1.0, v0, 1.0
	v_mul_f32_e32 v95, v94, v93
	v_fma_f32 v96, -v92, v95, v94
	v_fmac_f32_e32 v95, v96, v93
	v_fma_f32 v92, -v92, v95, v94
	v_div_fmas_f32 v92, v92, v93, v95
	v_div_fixup_f32 v0, v92, v0, 1.0
	s_nop 0
	v_cndmask_b32_e64 v0, 0, v0, s[0:1]
	s_and_b64 vcc, exec, s[12:13]
	s_cbranch_vccnz .Lmy_fin_m1_mode1
	s_waitcnt vmcnt(8)
	v_mul_f32_e32 v0, v250, v0
	s_waitcnt vmcnt(7)
	v_mul_f32_e32 v68, v32, v0
	v_lshlrev_b32_e32 v69, 16, v76
	v_mul_f32_e32 v70, v68, v69
	v_mul_f32_e32 v68, v33, v0
	v_and_b32_e32 v69, 0xffff0000, v76
	v_mul_f32_e32 v71, v68, v69
	v_mul_f32_e32 v68, v34, v0
	v_lshlrev_b32_e32 v69, 16, v77
	v_mul_f32_e32 v72, v68, v69
	v_mul_f32_e32 v68, v35, v0
	v_and_b32_e32 v69, 0xffff0000, v77
	v_mul_f32_e32 v73, v68, v69
	v_cvt_pk_bf16_f32 v98, v70, v71
	v_cvt_pk_bf16_f32 v99, v72, v73
	global_store_dwordx2 v[134:135], v[98:99], off
	s_waitcnt vmcnt(7)
	v_mul_f32_e32 v68, v28, v0
	v_lshlrev_b32_e32 v69, 16, v78
	v_mul_f32_e32 v70, v68, v69
	v_mul_f32_e32 v68, v29, v0
	v_and_b32_e32 v69, 0xffff0000, v78
	v_mul_f32_e32 v71, v68, v69
	v_mul_f32_e32 v68, v30, v0
	v_lshlrev_b32_e32 v69, 16, v79
	v_mul_f32_e32 v72, v68, v69
	v_mul_f32_e32 v68, v31, v0
	v_and_b32_e32 v69, 0xffff0000, v79
	v_mul_f32_e32 v73, v68, v69
	v_cvt_pk_bf16_f32 v98, v70, v71
	v_cvt_pk_bf16_f32 v99, v72, v73
	global_store_dwordx2 v[134:135], v[98:99], off offset:32
	s_waitcnt vmcnt(7)
	v_mul_f32_e32 v68, v24, v0
	v_lshlrev_b32_e32 v69, 16, v80
	v_mul_f32_e32 v70, v68, v69
	v_mul_f32_e32 v68, v25, v0
	v_and_b32_e32 v69, 0xffff0000, v80
	v_mul_f32_e32 v71, v68, v69
	v_mul_f32_e32 v68, v26, v0
	v_lshlrev_b32_e32 v69, 16, v81
	v_mul_f32_e32 v72, v68, v69
	v_mul_f32_e32 v68, v27, v0
	v_and_b32_e32 v69, 0xffff0000, v81
	v_mul_f32_e32 v73, v68, v69
	v_cvt_pk_bf16_f32 v98, v70, v71
	v_cvt_pk_bf16_f32 v99, v72, v73
	global_store_dwordx2 v[134:135], v[98:99], off offset:64
	s_waitcnt vmcnt(7)
	v_mul_f32_e32 v68, v20, v0
	v_lshlrev_b32_e32 v69, 16, v82
	v_mul_f32_e32 v70, v68, v69
	v_mul_f32_e32 v68, v21, v0
	v_and_b32_e32 v69, 0xffff0000, v82
	v_mul_f32_e32 v71, v68, v69
	v_mul_f32_e32 v68, v22, v0
	v_lshlrev_b32_e32 v69, 16, v83
	v_mul_f32_e32 v72, v68, v69
	v_mul_f32_e32 v68, v23, v0
	v_and_b32_e32 v69, 0xffff0000, v83
	v_mul_f32_e32 v73, v68, v69
	v_cvt_pk_bf16_f32 v98, v70, v71
	v_cvt_pk_bf16_f32 v99, v72, v73
	global_store_dwordx2 v[134:135], v[98:99], off offset:96
	s_waitcnt vmcnt(7)
	v_mul_f32_e32 v68, v16, v0
	v_lshlrev_b32_e32 v69, 16, v84
	v_mul_f32_e32 v70, v68, v69
	v_mul_f32_e32 v68, v17, v0
	v_and_b32_e32 v69, 0xffff0000, v84
	v_mul_f32_e32 v71, v68, v69
	v_mul_f32_e32 v68, v18, v0
	v_lshlrev_b32_e32 v69, 16, v85
	v_mul_f32_e32 v72, v68, v69
	v_mul_f32_e32 v68, v19, v0
	v_and_b32_e32 v69, 0xffff0000, v85
	v_mul_f32_e32 v73, v68, v69
	v_cvt_pk_bf16_f32 v98, v70, v71
	v_cvt_pk_bf16_f32 v99, v72, v73
	global_store_dwordx2 v[134:135], v[98:99], off offset:128
	s_waitcnt vmcnt(7)
	v_mul_f32_e32 v68, v12, v0
	v_lshlrev_b32_e32 v69, 16, v86
	v_mul_f32_e32 v70, v68, v69
	v_mul_f32_e32 v68, v13, v0
	v_and_b32_e32 v69, 0xffff0000, v86
	v_mul_f32_e32 v71, v68, v69
	v_mul_f32_e32 v68, v14, v0
	v_lshlrev_b32_e32 v69, 16, v87
	v_mul_f32_e32 v72, v68, v69
	v_mul_f32_e32 v68, v15, v0
	v_and_b32_e32 v69, 0xffff0000, v87
	v_mul_f32_e32 v73, v68, v69
	v_cvt_pk_bf16_f32 v98, v70, v71
	v_cvt_pk_bf16_f32 v99, v72, v73
	global_store_dwordx2 v[134:135], v[98:99], off offset:160
	s_waitcnt vmcnt(7)
	v_mul_f32_e32 v68, v8, v0
	v_lshlrev_b32_e32 v69, 16, v88
	v_mul_f32_e32 v70, v68, v69
	v_mul_f32_e32 v68, v9, v0
	v_and_b32_e32 v69, 0xffff0000, v88
	v_mul_f32_e32 v71, v68, v69
	v_mul_f32_e32 v68, v10, v0
	v_lshlrev_b32_e32 v69, 16, v89
	v_mul_f32_e32 v72, v68, v69
	v_mul_f32_e32 v68, v11, v0
	v_and_b32_e32 v69, 0xffff0000, v89
	v_mul_f32_e32 v73, v68, v69
	v_cvt_pk_bf16_f32 v98, v70, v71
	v_cvt_pk_bf16_f32 v99, v72, v73
	global_store_dwordx2 v[134:135], v[98:99], off offset:192
	s_waitcnt vmcnt(7)
	v_mul_f32_e32 v68, v4, v0
	v_lshlrev_b32_e32 v69, 16, v90
	v_mul_f32_e32 v70, v68, v69
	v_mul_f32_e32 v68, v5, v0
	v_and_b32_e32 v69, 0xffff0000, v90
	v_mul_f32_e32 v71, v68, v69
	v_mul_f32_e32 v68, v6, v0
	v_lshlrev_b32_e32 v69, 16, v91
	v_mul_f32_e32 v72, v68, v69
	v_mul_f32_e32 v68, v7, v0
	v_and_b32_e32 v69, 0xffff0000, v91
	v_mul_f32_e32 v73, v68, v69
	v_cvt_pk_bf16_f32 v98, v70, v71
	v_cvt_pk_bf16_f32 v99, v72, v73
	global_store_dwordx2 v[134:135], v[98:99], off offset:224
	s_branch .Lmy_fin_m1_done
.Lmy_fin_m1_mode1:
	s_waitcnt vmcnt(24)
	v_mul_f32_e32 v0, v250, v0
	s_waitcnt vmcnt(7)
	v_mul_f32_e32 v68, v32, v0
	v_lshlrev_b32_e32 v69, 16, v76
	v_mul_f32_e32 v70, v68, v69
	v_mul_f32_e32 v68, v33, v0
	v_and_b32_e32 v69, 0xffff0000, v76
	v_mul_f32_e32 v71, v68, v69
	v_mul_f32_e32 v68, v34, v0
	v_lshlrev_b32_e32 v69, 16, v77
	v_mul_f32_e32 v72, v68, v69
	v_mul_f32_e32 v68, v35, v0
	v_and_b32_e32 v69, 0xffff0000, v77
	v_mul_f32_e32 v73, v68, v69
	v_lshlrev_b32_e32 v74, 16, v218
	v_lshlrev_b32_e32 v75, 16, v234
	v_and_b32_e32 v92, 0xffff0000, v234
	v_and_b32_e32 v93, 0xffff0000, v218
	v_add_f32_e32 v74, v75, v74
	v_add_f32_e32 v93, v92, v93
	v_lshlrev_b32_e32 v94, 16, v219
	v_lshlrev_b32_e32 v75, 16, v235
	v_and_b32_e32 v92, 0xffff0000, v235
	v_and_b32_e32 v95, 0xffff0000, v219
	v_add_f32_e32 v95, v92, v95
	v_add_f32_e32 v93, v71, v93
	v_add_f32_e32 v94, v75, v94
	v_add_f32_e32 v95, v73, v95
	v_add_f32_e32 v74, v70, v74
	v_add_f32_e32 v94, v72, v94
	v_cvt_pk_bf16_f32 v98, v74, v93
	v_cvt_pk_bf16_f32 v99, v94, v95
	global_store_dwordx2 v[134:135], v[98:99], off
	s_waitcnt vmcnt(7)
	v_mul_f32_e32 v68, v28, v0
	v_lshlrev_b32_e32 v69, 16, v78
	v_mul_f32_e32 v70, v68, v69
	v_mul_f32_e32 v68, v29, v0
	v_and_b32_e32 v69, 0xffff0000, v78
	v_mul_f32_e32 v71, v68, v69
	v_mul_f32_e32 v68, v30, v0
	v_lshlrev_b32_e32 v69, 16, v79
	v_mul_f32_e32 v72, v68, v69
	v_mul_f32_e32 v68, v31, v0
	v_and_b32_e32 v69, 0xffff0000, v79
	v_mul_f32_e32 v73, v68, v69
	v_lshlrev_b32_e32 v74, 16, v220
	v_lshlrev_b32_e32 v75, 16, v236
	v_and_b32_e32 v92, 0xffff0000, v236
	v_and_b32_e32 v93, 0xffff0000, v220
	v_add_f32_e32 v74, v75, v74
	v_add_f32_e32 v93, v92, v93
	v_lshlrev_b32_e32 v94, 16, v221
	v_lshlrev_b32_e32 v75, 16, v237
	v_and_b32_e32 v92, 0xffff0000, v237
	v_and_b32_e32 v95, 0xffff0000, v221
	v_add_f32_e32 v95, v92, v95
	v_add_f32_e32 v93, v71, v93
	v_add_f32_e32 v94, v75, v94
	v_add_f32_e32 v95, v73, v95
	v_add_f32_e32 v74, v70, v74
	v_add_f32_e32 v94, v72, v94
	v_cvt_pk_bf16_f32 v98, v74, v93
	v_cvt_pk_bf16_f32 v99, v94, v95
	global_store_dwordx2 v[134:135], v[98:99], off offset:32
	s_waitcnt vmcnt(7)
	v_mul_f32_e32 v68, v24, v0
	v_lshlrev_b32_e32 v69, 16, v80
	v_mul_f32_e32 v70, v68, v69
	v_mul_f32_e32 v68, v25, v0
	v_and_b32_e32 v69, 0xffff0000, v80
	v_mul_f32_e32 v71, v68, v69
	v_mul_f32_e32 v68, v26, v0
	v_lshlrev_b32_e32 v69, 16, v81
	v_mul_f32_e32 v72, v68, v69
	v_mul_f32_e32 v68, v27, v0
	v_and_b32_e32 v69, 0xffff0000, v81
	v_mul_f32_e32 v73, v68, v69
	v_lshlrev_b32_e32 v74, 16, v222
	v_lshlrev_b32_e32 v75, 16, v238
	v_and_b32_e32 v92, 0xffff0000, v238
	v_and_b32_e32 v93, 0xffff0000, v222
	v_add_f32_e32 v74, v75, v74
	v_add_f32_e32 v93, v92, v93
	v_lshlrev_b32_e32 v94, 16, v223
	v_lshlrev_b32_e32 v75, 16, v239
	v_and_b32_e32 v92, 0xffff0000, v239
	v_and_b32_e32 v95, 0xffff0000, v223
	v_add_f32_e32 v95, v92, v95
	v_add_f32_e32 v93, v71, v93
	v_add_f32_e32 v94, v75, v94
	v_add_f32_e32 v95, v73, v95
	v_add_f32_e32 v74, v70, v74
	v_add_f32_e32 v94, v72, v94
	v_cvt_pk_bf16_f32 v98, v74, v93
	v_cvt_pk_bf16_f32 v99, v94, v95
	global_store_dwordx2 v[134:135], v[98:99], off offset:64
	s_waitcnt vmcnt(7)
	v_mul_f32_e32 v68, v20, v0
	v_lshlrev_b32_e32 v69, 16, v82
	v_mul_f32_e32 v70, v68, v69
	v_mul_f32_e32 v68, v21, v0
	v_and_b32_e32 v69, 0xffff0000, v82
	v_mul_f32_e32 v71, v68, v69
	v_mul_f32_e32 v68, v22, v0
	v_lshlrev_b32_e32 v69, 16, v83
	v_mul_f32_e32 v72, v68, v69
	v_mul_f32_e32 v68, v23, v0
	v_and_b32_e32 v69, 0xffff0000, v83
	v_mul_f32_e32 v73, v68, v69
	v_lshlrev_b32_e32 v74, 16, v224
	v_lshlrev_b32_e32 v75, 16, v240
	v_and_b32_e32 v92, 0xffff0000, v240
	v_and_b32_e32 v93, 0xffff0000, v224
	v_add_f32_e32 v74, v75, v74
	v_add_f32_e32 v93, v92, v93
	v_lshlrev_b32_e32 v94, 16, v225
	v_lshlrev_b32_e32 v75, 16, v241
	v_and_b32_e32 v92, 0xffff0000, v241
	v_and_b32_e32 v95, 0xffff0000, v225
	v_add_f32_e32 v95, v92, v95
	v_add_f32_e32 v93, v71, v93
	v_add_f32_e32 v94, v75, v94
	v_add_f32_e32 v95, v73, v95
	v_add_f32_e32 v74, v70, v74
	v_add_f32_e32 v94, v72, v94
	v_cvt_pk_bf16_f32 v98, v74, v93
	v_cvt_pk_bf16_f32 v99, v94, v95
	global_store_dwordx2 v[134:135], v[98:99], off offset:96
	s_waitcnt vmcnt(7)
	v_mul_f32_e32 v68, v16, v0
	v_lshlrev_b32_e32 v69, 16, v84
	v_mul_f32_e32 v70, v68, v69
	v_mul_f32_e32 v68, v17, v0
	v_and_b32_e32 v69, 0xffff0000, v84
	v_mul_f32_e32 v71, v68, v69
	v_mul_f32_e32 v68, v18, v0
	v_lshlrev_b32_e32 v69, 16, v85
	v_mul_f32_e32 v72, v68, v69
	v_mul_f32_e32 v68, v19, v0
	v_and_b32_e32 v69, 0xffff0000, v85
	v_mul_f32_e32 v73, v68, v69
	v_lshlrev_b32_e32 v74, 16, v226
	v_lshlrev_b32_e32 v75, 16, v242
	v_and_b32_e32 v92, 0xffff0000, v242
	v_and_b32_e32 v93, 0xffff0000, v226
	v_add_f32_e32 v74, v75, v74
	v_add_f32_e32 v93, v92, v93
	v_lshlrev_b32_e32 v94, 16, v227
	v_lshlrev_b32_e32 v75, 16, v243
	v_and_b32_e32 v92, 0xffff0000, v243
	v_and_b32_e32 v95, 0xffff0000, v227
	v_add_f32_e32 v95, v92, v95
	v_add_f32_e32 v93, v71, v93
	v_add_f32_e32 v94, v75, v94
	v_add_f32_e32 v95, v73, v95
	v_add_f32_e32 v74, v70, v74
	v_add_f32_e32 v94, v72, v94
	v_cvt_pk_bf16_f32 v98, v74, v93
	v_cvt_pk_bf16_f32 v99, v94, v95
	global_store_dwordx2 v[134:135], v[98:99], off offset:128
	s_waitcnt vmcnt(7)
	v_mul_f32_e32 v68, v12, v0
	v_lshlrev_b32_e32 v69, 16, v86
	v_mul_f32_e32 v70, v68, v69
	v_mul_f32_e32 v68, v13, v0
	v_and_b32_e32 v69, 0xffff0000, v86
	v_mul_f32_e32 v71, v68, v69
	v_mul_f32_e32 v68, v14, v0
	v_lshlrev_b32_e32 v69, 16, v87
	v_mul_f32_e32 v72, v68, v69
	v_mul_f32_e32 v68, v15, v0
	v_and_b32_e32 v69, 0xffff0000, v87
	v_mul_f32_e32 v73, v68, v69
	v_lshlrev_b32_e32 v74, 16, v228
	v_lshlrev_b32_e32 v75, 16, v244
	v_and_b32_e32 v92, 0xffff0000, v244
	v_and_b32_e32 v93, 0xffff0000, v228
	v_add_f32_e32 v74, v75, v74
	v_add_f32_e32 v93, v92, v93
	v_lshlrev_b32_e32 v94, 16, v229
	v_lshlrev_b32_e32 v75, 16, v245
	v_and_b32_e32 v92, 0xffff0000, v245
	v_and_b32_e32 v95, 0xffff0000, v229
	v_add_f32_e32 v95, v92, v95
	v_add_f32_e32 v93, v71, v93
	v_add_f32_e32 v94, v75, v94
	v_add_f32_e32 v95, v73, v95
	v_add_f32_e32 v74, v70, v74
	v_add_f32_e32 v94, v72, v94
	v_cvt_pk_bf16_f32 v98, v74, v93
	v_cvt_pk_bf16_f32 v99, v94, v95
	global_store_dwordx2 v[134:135], v[98:99], off offset:160
	s_waitcnt vmcnt(7)
	v_mul_f32_e32 v68, v8, v0
	v_lshlrev_b32_e32 v69, 16, v88
	v_mul_f32_e32 v70, v68, v69
	v_mul_f32_e32 v68, v9, v0
	v_and_b32_e32 v69, 0xffff0000, v88
	v_mul_f32_e32 v71, v68, v69
	v_mul_f32_e32 v68, v10, v0
	v_lshlrev_b32_e32 v69, 16, v89
	v_mul_f32_e32 v72, v68, v69
	v_mul_f32_e32 v68, v11, v0
	v_and_b32_e32 v69, 0xffff0000, v89
	v_mul_f32_e32 v73, v68, v69
	v_lshlrev_b32_e32 v74, 16, v230
	v_lshlrev_b32_e32 v75, 16, v246
	v_and_b32_e32 v92, 0xffff0000, v246
	v_and_b32_e32 v93, 0xffff0000, v230
	v_add_f32_e32 v74, v75, v74
	v_add_f32_e32 v93, v92, v93
	v_lshlrev_b32_e32 v94, 16, v231
	v_lshlrev_b32_e32 v75, 16, v247
	v_and_b32_e32 v92, 0xffff0000, v247
	v_and_b32_e32 v95, 0xffff0000, v231
	v_add_f32_e32 v95, v92, v95
	v_add_f32_e32 v93, v71, v93
	v_add_f32_e32 v94, v75, v94
	v_add_f32_e32 v95, v73, v95
	v_add_f32_e32 v74, v70, v74
	v_add_f32_e32 v94, v72, v94
	v_cvt_pk_bf16_f32 v98, v74, v93
	v_cvt_pk_bf16_f32 v99, v94, v95
	global_store_dwordx2 v[134:135], v[98:99], off offset:192
	s_waitcnt vmcnt(7)
	v_mul_f32_e32 v68, v4, v0
	v_lshlrev_b32_e32 v69, 16, v90
	v_mul_f32_e32 v70, v68, v69
	v_mul_f32_e32 v68, v5, v0
	v_and_b32_e32 v69, 0xffff0000, v90
	v_mul_f32_e32 v71, v68, v69
	v_mul_f32_e32 v68, v6, v0
	v_lshlrev_b32_e32 v69, 16, v91
	v_mul_f32_e32 v72, v68, v69
	v_mul_f32_e32 v68, v7, v0
	v_and_b32_e32 v69, 0xffff0000, v91
	v_mul_f32_e32 v73, v68, v69
	v_lshlrev_b32_e32 v74, 16, v232
	v_lshlrev_b32_e32 v75, 16, v248
	v_and_b32_e32 v92, 0xffff0000, v248
	v_and_b32_e32 v93, 0xffff0000, v232
	v_add_f32_e32 v74, v75, v74
	v_add_f32_e32 v93, v92, v93
	v_lshlrev_b32_e32 v94, 16, v233
	v_lshlrev_b32_e32 v75, 16, v249
	v_and_b32_e32 v92, 0xffff0000, v249
	v_and_b32_e32 v95, 0xffff0000, v233
	v_add_f32_e32 v95, v92, v95
	v_add_f32_e32 v93, v71, v93
	v_add_f32_e32 v94, v75, v94
	v_add_f32_e32 v95, v73, v95
	v_add_f32_e32 v74, v70, v74
	v_add_f32_e32 v94, v72, v94
	v_cvt_pk_bf16_f32 v98, v74, v93
	v_cvt_pk_bf16_f32 v99, v94, v95
	global_store_dwordx2 v[134:135], v[98:99], off offset:224
.Lmy_fin_m1_done:
	s_branch .LBB0_58
.LBB0_140:
	s_mov_b64 s[2:3], 0
	v_writelane_b32 v255, s2, 4
	s_nop 1
	v_writelane_b32 v255, s3, 5
	s_cbranch_execnz .LBB0_585

.LBB0_398:
	s_cmp_lt_u32 s76, 4
	s_cselect_b32 s0, s20, s15
	v_add_u32_e32 v190, s0, v102
	s_lshl_b32 s0, s76, 2
	v_and_or_b32 v93, s0, 12, v190
	v_subrev_u32_e32 v0, 28, v93
	v_ashrrev_i32_e32 v0, 4, v0
	v_add_u32_e32 v0, 16, v0
	v_ashrrev_i32_e32 v0, 4, v0
	v_cmp_lt_i32_e32 vcc, 27, v93
	s_nop 1
	v_cndmask_b32_e32 v0, 0, v0, vcc
	s_nop 0
	v_readfirstlane_b32 s0, v0
	s_cmp_eq_u32 s0, 0
	s_cbranch_scc1 .Lmy_qk_z0
	ds_read_b128 v[192:195], v110
	ds_read_b128 v[196:199], v110 offset:4352
	ds_read_b128 v[200:203], v110 offset:64
	ds_read_b128 v[204:207], v110 offset:4416
	ds_read_b128 v[208:211], v110 offset:128
	ds_read_b128 v[212:215], v110 offset:4480
	ds_read_b128 v[216:219], v110 offset:192
	ds_read_b128 v[220:223], v110 offset:4544
	ds_read_b128 v[224:227], v110 offset:8704
	ds_read_b128 v[228:231], v110 offset:13056
	ds_read_b128 v[232:235], v110 offset:8768
	ds_read_b128 v[236:239], v110 offset:13120
	s_waitcnt vmcnt(0)
	s_waitcnt lgkmcnt(11)
	v_mfma_f32_16x16x32_bf16 v[24:27], v[192:195], v[16:19], 0
	ds_read_b128 v[192:195], v110 offset:8832
	s_waitcnt lgkmcnt(11)
	v_mfma_f32_16x16x32_bf16 v[28:31], v[196:199], v[16:19], 0
	ds_read_b128 v[196:199], v110 offset:13184
	s_waitcnt lgkmcnt(11)
	v_mfma_f32_16x16x32_bf16 v[24:27], v[200:203], v[12:15], v[24:27]
	ds_read_b128 v[200:203], v110 offset:8896
	s_waitcnt lgkmcnt(11)
	v_mfma_f32_16x16x32_bf16 v[28:31], v[204:207], v[12:15], v[28:31]
	ds_read_b128 v[204:207], v110 offset:13248
	s_waitcnt lgkmcnt(11)
	v_mfma_f32_16x16x32_bf16 v[24:27], v[208:211], v[8:11], v[24:27]
	ds_read_b128 v[208:211], v110 offset:17408
	s_waitcnt lgkmcnt(11)
	v_mfma_f32_16x16x32_bf16 v[28:31], v[212:215], v[8:11], v[28:31]
	ds_read_b128 v[212:215], v110 offset:21760
	s_waitcnt lgkmcnt(11)
	v_mfma_f32_16x16x32_bf16 v[24:27], v[216:219], v[4:7], v[24:27]
	ds_read_b128 v[216:219], v110 offset:17472
	s_waitcnt lgkmcnt(11)
	v_mfma_f32_16x16x32_bf16 v[28:31], v[220:223], v[4:7], v[28:31]
	ds_read_b128 v[220:223], v110 offset:21824
	s_cmp_le_u32 s0, 2
	s_cbranch_scc1 .Lmy_qk_z1
	s_waitcnt lgkmcnt(11)
	v_mfma_f32_16x16x32_bf16 v[20:23], v[224:227], v[16:19], 0
	ds_read_b128 v[224:227], v110 offset:17536
	s_waitcnt lgkmcnt(11)
	v_mfma_f32_16x16x32_bf16 v[36:39], v[228:231], v[16:19], 0
	ds_read_b128 v[228:231], v110 offset:21888
	s_waitcnt lgkmcnt(11)
	v_mfma_f32_16x16x32_bf16 v[20:23], v[232:235], v[12:15], v[20:23]
	ds_read_b128 v[232:235], v110 offset:17600
	s_waitcnt lgkmcnt(11)
	v_mfma_f32_16x16x32_bf16 v[36:39], v[236:239], v[12:15], v[36:39]
	ds_read_b128 v[236:239], v110 offset:21952
	s_waitcnt lgkmcnt(11)
	v_mfma_f32_16x16x32_bf16 v[20:23], v[192:195], v[8:11], v[20:23]
	ds_read_b128 v[192:195], v110 offset:26112
	s_waitcnt lgkmcnt(11)
	v_mfma_f32_16x16x32_bf16 v[36:39], v[196:199], v[8:11], v[36:39]
	ds_read_b128 v[196:199], v110 offset:30464
	s_waitcnt lgkmcnt(11)
	v_mfma_f32_16x16x32_bf16 v[20:23], v[200:203], v[4:7], v[20:23]
	ds_read_b128 v[200:203], v110 offset:26176
	s_waitcnt lgkmcnt(11)
	v_mfma_f32_16x16x32_bf16 v[36:39], v[204:207], v[4:7], v[36:39]
	ds_read_b128 v[204:207], v110 offset:30528
	s_cmp_le_u32 s0, 4
	s_cbranch_scc1 .Lmy_qk_z2
	s_waitcnt lgkmcnt(11)
	v_mfma_f32_16x16x32_bf16 v[52:55], v[208:211], v[16:19], 0
	ds_read_b128 v[208:211], v110 offset:26240
	s_waitcnt lgkmcnt(11)
	v_mfma_f32_16x16x32_bf16 v[40:43], v[212:215], v[16:19], 0
	ds_read_b128 v[212:215], v110 offset:30592
	s_waitcnt lgkmcnt(11)
	v_mfma_f32_16x16x32_bf16 v[52:55], v[216:219], v[12:15], v[52:55]
	ds_read_b128 v[216:219], v110 offset:26304
	s_waitcnt lgkmcnt(11)
	v_mfma_f32_16x16x32_bf16 v[40:43], v[220:223], v[12:15], v[40:43]
	ds_read_b128 v[220:223], v110 offset:30656
	s_waitcnt lgkmcnt(11)
	v_mfma_f32_16x16x32_bf16 v[52:55], v[224:227], v[8:11], v[52:55]
	ds_read_b128 v[224:227], v110 offset:34816
	s_waitcnt lgkmcnt(11)
	v_mfma_f32_16x16x32_bf16 v[40:43], v[228:231], v[8:11], v[40:43]
	ds_read_b128 v[228:231], v110 offset:39168
	s_waitcnt lgkmcnt(11)
	v_mfma_f32_16x16x32_bf16 v[52:55], v[232:235], v[4:7], v[52:55]
	ds_read_b128 v[232:235], v110 offset:34880
	s_waitcnt lgkmcnt(11)
	v_mfma_f32_16x16x32_bf16 v[40:43], v[236:239], v[4:7], v[40:43]
	ds_read_b128 v[236:239], v110 offset:39232
	s_cmp_le_u32 s0, 6
	s_cbranch_scc1 .Lmy_qk_z3
	s_waitcnt lgkmcnt(11)
	v_mfma_f32_16x16x32_bf16 v[32:35], v[192:195], v[16:19], 0
	ds_read_b128 v[192:195], v110 offset:34944
	s_waitcnt lgkmcnt(11)
	v_mfma_f32_16x16x32_bf16 v[44:47], v[196:199], v[16:19], 0
	ds_read_b128 v[196:199], v110 offset:39296
	s_waitcnt lgkmcnt(11)
	v_mfma_f32_16x16x32_bf16 v[32:35], v[200:203], v[12:15], v[32:35]
	ds_read_b128 v[200:203], v110 offset:35008
	s_waitcnt lgkmcnt(11)
	v_mfma_f32_16x16x32_bf16 v[44:47], v[204:207], v[12:15], v[44:47]
	ds_read_b128 v[204:207], v110 offset:39360
	s_waitcnt lgkmcnt(11)
	v_mfma_f32_16x16x32_bf16 v[32:35], v[208:211], v[8:11], v[32:35]
	ds_read_b128 v[208:211], v110 offset:43520
	s_waitcnt lgkmcnt(11)
	v_mfma_f32_16x16x32_bf16 v[44:47], v[212:215], v[8:11], v[44:47]
	ds_read_b128 v[212:215], v110 offset:47872
	s_waitcnt lgkmcnt(11)
	v_mfma_f32_16x16x32_bf16 v[32:35], v[216:219], v[4:7], v[32:35]
	ds_read_b128 v[216:219], v110 offset:43584
	s_waitcnt lgkmcnt(11)
	v_mfma_f32_16x16x32_bf16 v[44:47], v[220:223], v[4:7], v[44:47]
	ds_read_b128 v[220:223], v110 offset:47936
	s_cmp_le_u32 s0, 8
	s_cbranch_scc1 .Lmy_qk_z4
	s_waitcnt lgkmcnt(11)
	v_mfma_f32_16x16x32_bf16 v[60:63], v[224:227], v[16:19], 0
	ds_read_b128 v[224:227], v110 offset:43648
	s_waitcnt lgkmcnt(11)
	v_mfma_f32_16x16x32_bf16 v[56:59], v[228:231], v[16:19], 0
	ds_read_b128 v[228:231], v110 offset:48000
	s_waitcnt lgkmcnt(11)
	v_mfma_f32_16x16x32_bf16 v[60:63], v[232:235], v[12:15], v[60:63]
	ds_read_b128 v[232:235], v110 offset:43712
	s_waitcnt lgkmcnt(11)
	v_mfma_f32_16x16x32_bf16 v[56:59], v[236:239], v[12:15], v[56:59]
	ds_read_b128 v[236:239], v110 offset:48064
	s_waitcnt lgkmcnt(11)
	v_mfma_f32_16x16x32_bf16 v[60:63], v[192:195], v[8:11], v[60:63]
	ds_read_b128 v[192:195], v110 offset:52224
	s_waitcnt lgkmcnt(11)
	v_mfma_f32_16x16x32_bf16 v[56:59], v[196:199], v[8:11], v[56:59]
	ds_read_b128 v[196:199], v110 offset:56576
	s_waitcnt lgkmcnt(11)
	v_mfma_f32_16x16x32_bf16 v[60:63], v[200:203], v[4:7], v[60:63]
	ds_read_b128 v[200:203], v110 offset:52288
	s_waitcnt lgkmcnt(11)
	v_mfma_f32_16x16x32_bf16 v[56:59], v[204:207], v[4:7], v[56:59]
	ds_read_b128 v[204:207], v110 offset:56640
	s_cmp_le_u32 s0, 10
	s_cbranch_scc1 .Lmy_qk_z5
	s_waitcnt lgkmcnt(11)
	v_mfma_f32_16x16x32_bf16 v[48:51], v[208:211], v[16:19], 0
	ds_read_b128 v[208:211], v110 offset:52352
	s_waitcnt lgkmcnt(11)
	v_mfma_f32_16x16x32_bf16 v[68:71], v[212:215], v[16:19], 0
	ds_read_b128 v[212:215], v110 offset:56704
	s_waitcnt lgkmcnt(11)
	v_mfma_f32_16x16x32_bf16 v[48:51], v[216:219], v[12:15], v[48:51]
	ds_read_b128 v[216:219], v110 offset:52416
	s_waitcnt lgkmcnt(11)
	v_mfma_f32_16x16x32_bf16 v[68:71], v[220:223], v[12:15], v[68:71]
	ds_read_b128 v[220:223], v110 offset:56768
	s_waitcnt lgkmcnt(11)
	v_mfma_f32_16x16x32_bf16 v[48:51], v[224:227], v[8:11], v[48:51]
	ds_read_b128 v[224:227], v110 offset:60928
	s_waitcnt lgkmcnt(11)
	v_mfma_f32_16x16x32_bf16 v[68:71], v[228:231], v[8:11], v[68:71]
	ds_read_b128 v[228:231], v110 offset:65280
	s_waitcnt lgkmcnt(11)
	v_mfma_f32_16x16x32_bf16 v[48:51], v[232:235], v[4:7], v[48:51]
	ds_read_b128 v[232:235], v110 offset:60992
	s_waitcnt lgkmcnt(11)
	v_mfma_f32_16x16x32_bf16 v[68:71], v[236:239], v[4:7], v[68:71]
	ds_read_b128 v[236:239], v110 offset:65344
	s_cmp_le_u32 s0, 12
	s_cbranch_scc1 .Lmy_qk_z6
	s_waitcnt lgkmcnt(11)
	v_mfma_f32_16x16x32_bf16 v[76:79], v[192:195], v[16:19], 0
	ds_read_b128 v[192:195], v110 offset:61056
	s_waitcnt lgkmcnt(11)
	v_mfma_f32_16x16x32_bf16 v[72:75], v[196:199], v[16:19], 0
	ds_read_b128 v[196:199], v110 offset:65408
	s_waitcnt lgkmcnt(11)
	v_mfma_f32_16x16x32_bf16 v[76:79], v[200:203], v[12:15], v[76:79]
	ds_read_b128 v[200:203], v110 offset:61120
	s_waitcnt lgkmcnt(11)
	v_mfma_f32_16x16x32_bf16 v[72:75], v[204:207], v[12:15], v[72:75]
	ds_read_b128 v[204:207], v110 offset:65472
	s_waitcnt lgkmcnt(11)
	v_mfma_f32_16x16x32_bf16 v[76:79], v[208:211], v[8:11], v[76:79]
	s_waitcnt lgkmcnt(10)
	v_mfma_f32_16x16x32_bf16 v[72:75], v[212:215], v[8:11], v[72:75]
	s_waitcnt lgkmcnt(9)
	v_mfma_f32_16x16x32_bf16 v[76:79], v[216:219], v[4:7], v[76:79]
	s_waitcnt lgkmcnt(8)
	v_mfma_f32_16x16x32_bf16 v[72:75], v[220:223], v[4:7], v[72:75]
	s_cmp_le_u32 s0, 14
	s_cbranch_scc1 .Lmy_qk_z7
	s_waitcnt lgkmcnt(7)
	v_mfma_f32_16x16x32_bf16 v[64:67], v[224:227], v[16:19], 0
	s_waitcnt lgkmcnt(6)
	v_mfma_f32_16x16x32_bf16 v[80:83], v[228:231], v[16:19], 0
	s_waitcnt lgkmcnt(5)
	v_mfma_f32_16x16x32_bf16 v[64:67], v[232:235], v[12:15], v[64:67]
	s_waitcnt lgkmcnt(4)
	v_mfma_f32_16x16x32_bf16 v[80:83], v[236:239], v[12:15], v[80:83]
	s_waitcnt lgkmcnt(3)
	v_mfma_f32_16x16x32_bf16 v[64:67], v[192:195], v[8:11], v[64:67]
	s_waitcnt lgkmcnt(2)
	v_mfma_f32_16x16x32_bf16 v[80:83], v[196:199], v[8:11], v[80:83]
	s_waitcnt lgkmcnt(1)
	v_mfma_f32_16x16x32_bf16 v[64:67], v[200:203], v[4:7], v[64:67]
	s_waitcnt lgkmcnt(0)
	v_mfma_f32_16x16x32_bf16 v[80:83], v[204:207], v[4:7], v[80:83]
	s_branch .Lmy_qk_done
.Lmy_qk_z0:
	v_mov_b32_e32 v24, 0
	v_mov_b32_e32 v25, 0
	v_mov_b32_e32 v26, 0
	v_mov_b32_e32 v27, 0
	v_mov_b32_e32 v28, 0
	v_mov_b32_e32 v29, 0
	v_mov_b32_e32 v30, 0
	v_mov_b32_e32 v31, 0
.Lmy_qk_z1:
	v_mov_b32_e32 v20, 0
	v_mov_b32_e32 v21, 0
	v_mov_b32_e32 v22, 0
	v_mov_b32_e32 v23, 0
	v_mov_b32_e32 v36, 0
	v_mov_b32_e32 v37, 0
	v_mov_b32_e32 v38, 0
	v_mov_b32_e32 v39, 0
.Lmy_qk_z2:
	v_mov_b32_e32 v52, 0
	v_mov_b32_e32 v53, 0
	v_mov_b32_e32 v54, 0
	v_mov_b32_e32 v55, 0
	v_mov_b32_e32 v40, 0
	v_mov_b32_e32 v41, 0
	v_mov_b32_e32 v42, 0
	v_mov_b32_e32 v43, 0
.Lmy_qk_z3:
	v_mov_b32_e32 v32, 0
	v_mov_b32_e32 v33, 0
	v_mov_b32_e32 v34, 0
	v_mov_b32_e32 v35, 0
	v_mov_b32_e32 v44, 0
	v_mov_b32_e32 v45, 0
	v_mov_b32_e32 v46, 0
	v_mov_b32_e32 v47, 0
.Lmy_qk_z4:
	v_mov_b32_e32 v60, 0
	v_mov_b32_e32 v61, 0
	v_mov_b32_e32 v62, 0
	v_mov_b32_e32 v63, 0
	v_mov_b32_e32 v56, 0
	v_mov_b32_e32 v57, 0
	v_mov_b32_e32 v58, 0
	v_mov_b32_e32 v59, 0
.Lmy_qk_z5:
	v_mov_b32_e32 v48, 0
	v_mov_b32_e32 v49, 0
	v_mov_b32_e32 v50, 0
	v_mov_b32_e32 v51, 0
	v_mov_b32_e32 v68, 0
	v_mov_b32_e32 v69, 0
	v_mov_b32_e32 v70, 0
	v_mov_b32_e32 v71, 0
.Lmy_qk_z6:
	v_mov_b32_e32 v76, 0
	v_mov_b32_e32 v77, 0
	v_mov_b32_e32 v78, 0
	v_mov_b32_e32 v79, 0
	v_mov_b32_e32 v72, 0
	v_mov_b32_e32 v73, 0
	v_mov_b32_e32 v74, 0
	v_mov_b32_e32 v75, 0
.Lmy_qk_z7:
	v_mov_b32_e32 v64, 0
	v_mov_b32_e32 v65, 0
	v_mov_b32_e32 v66, 0
	v_mov_b32_e32 v67, 0
	v_mov_b32_e32 v80, 0
	v_mov_b32_e32 v81, 0
	v_mov_b32_e32 v82, 0
	v_mov_b32_e32 v83, 0
.Lmy_qk_done:
	s_waitcnt lgkmcnt(0)
	v_or_b32_e32 v2, v93, v103
	v_subrev_u32_e32 v3, 31, v2
	v_ashrrev_i32_e32 v3, 4, v3
	v_add_u32_e32 v3, 1, v3
	v_cmp_lt_i32_e32 vcc, 30, v2
	s_waitcnt vmcnt(0)
	v_max_f32_e32 v4, v24, v24
	v_max_f32_e32 v4, 0xf149f2ca, v4
	v_cndmask_b32_e32 v3, 0, v3, vcc
	v_cmp_lt_i32_e64 s[72:73], v111, v3
	v_cmp_lt_i32_e32 vcc, v105, v3
	v_cmp_lt_i32_e64 s[70:71], v112, v3
	v_cndmask_b32_e64 v5, v146, v25, s[72:73]
	v_cndmask_b32_e32 v4, v146, v4, vcc
	v_max_f32_e32 v5, v5, v5
	v_cmp_lt_i32_e64 s[68:69], v113, v3
	v_max_f32_e32 v4, v4, v5
	v_cndmask_b32_e64 v5, v146, v26, s[70:71]
	v_cndmask_b32_e64 v6, v146, v27, s[68:69]
	v_cmp_lt_i32_e64 s[66:67], v114, v3
	v_cmp_lt_i32_e64 s[64:65], v115, v3
	v_max3_f32 v4, v4, v5, v6
	v_cndmask_b32_e64 v5, v146, v28, s[66:67]
	v_cndmask_b32_e64 v6, v146, v29, s[64:65]
	v_cmp_lt_i32_e64 s[62:63], v116, v3
	v_cmp_lt_i32_e64 s[60:61], v117, v3
	v_max3_f32 v4, v4, v5, v6
	v_cndmask_b32_e64 v5, v146, v30, s[62:63]
	v_cndmask_b32_e64 v6, v146, v31, s[60:61]
	v_cmp_lt_i32_e64 s[58:59], v118, v3
	v_cmp_lt_i32_e64 s[56:57], v119, v3
	v_max3_f32 v4, v4, v5, v6
	v_cndmask_b32_e64 v5, v146, v20, s[58:59]
	v_cndmask_b32_e64 v6, v146, v21, s[56:57]
	v_cmp_lt_i32_e64 s[54:55], v120, v3
	v_cmp_lt_i32_e64 s[52:53], v121, v3
	v_max3_f32 v4, v4, v5, v6
	v_cndmask_b32_e64 v5, v146, v22, s[54:55]
	v_cndmask_b32_e64 v6, v146, v23, s[52:53]
	v_cmp_lt_i32_e64 s[50:51], v122, v3
	v_cmp_lt_i32_e64 s[48:49], v123, v3
	v_max3_f32 v4, v4, v5, v6
	v_cndmask_b32_e64 v5, v146, v36, s[50:51]
	v_cndmask_b32_e64 v6, v146, v37, s[48:49]
	v_cmp_lt_i32_e64 s[46:47], v124, v3
	v_cmp_lt_i32_e64 s[44:45], v125, v3
	v_max3_f32 v4, v4, v5, v6
	v_cndmask_b32_e64 v5, v146, v38, s[46:47]
	v_cndmask_b32_e64 v6, v146, v39, s[44:45]
	v_cmp_lt_i32_e64 s[42:43], v126, v3
	v_cmp_lt_i32_e64 s[40:41], v127, v3
	v_max3_f32 v4, v4, v5, v6
	v_cndmask_b32_e64 v5, v146, v52, s[42:43]
	v_cndmask_b32_e64 v6, v146, v53, s[40:41]
	v_cmp_lt_i32_e64 s[0:1], v128, v3
	v_cmp_lt_i32_e64 s[38:39], v129, v3
	v_max3_f32 v4, v4, v5, v6
	v_cndmask_b32_e64 v5, v146, v54, s[0:1]
	v_cndmask_b32_e64 v6, v146, v55, s[38:39]
	v_cmp_lt_i32_e64 s[36:37], v132, v3
	v_cmp_lt_i32_e64 s[34:35], v133, v3
	v_max3_f32 v4, v4, v5, v6
	v_cndmask_b32_e64 v5, v146, v40, s[36:37]
	v_cndmask_b32_e64 v6, v146, v41, s[34:35]
	v_cmp_lt_i32_e64 s[30:31], v134, v3
	v_cmp_lt_i32_e64 s[28:29], v135, v3
	v_max3_f32 v4, v4, v5, v6
	v_cndmask_b32_e64 v5, v146, v42, s[30:31]
	v_cndmask_b32_e64 v6, v146, v43, s[28:29]
	v_cmp_lt_i32_e64 s[26:27], v136, v3
	v_cmp_lt_i32_e64 s[24:25], v137, v3
	v_max3_f32 v4, v4, v5, v6
	v_cndmask_b32_e64 v5, v146, v32, s[26:27]
	v_cndmask_b32_e64 v6, v146, v33, s[24:25]
	v_cmp_lt_i32_e64 s[22:23], v138, v3
	v_cmp_lt_i32_e64 s[20:21], v139, v3
	v_max3_f32 v4, v4, v5, v6
	v_cndmask_b32_e64 v5, v146, v34, s[22:23]
	v_cndmask_b32_e64 v6, v146, v35, s[20:21]
	v_cmp_lt_i32_e64 s[18:19], v140, v3
	v_cmp_lt_i32_e64 s[16:17], v141, v3
	v_max3_f32 v4, v4, v5, v6
	v_cndmask_b32_e64 v5, v146, v44, s[18:19]
	v_cndmask_b32_e64 v6, v146, v45, s[16:17]
	v_cmp_lt_i32_e64 s[14:15], v142, v3
	v_cmp_lt_i32_e64 s[12:13], v143, v3
	v_max3_f32 v4, v4, v5, v6
	v_cndmask_b32_e64 v5, v146, v46, s[14:15]
	v_cndmask_b32_e64 v6, v146, v47, s[12:13]
	v_cmp_lt_i32_e64 s[10:11], v153, v3
	v_cmp_lt_i32_e64 s[8:9], v154, v3
	v_max3_f32 v4, v4, v5, v6
	v_cndmask_b32_e64 v5, v146, v60, s[10:11]
	v_cndmask_b32_e64 v6, v146, v61, s[8:9]
	v_cmp_lt_i32_e64 s[6:7], v155, v3
	v_cmp_lt_i32_e64 s[4:5], v156, v3
	v_max3_f32 v4, v4, v5, v6
	v_cndmask_b32_e64 v5, v146, v62, s[6:7]
	v_cndmask_b32_e64 v6, v146, v63, s[4:5]
	v_cmp_lt_i32_e64 s[94:95], v157, v3
	v_cmp_lt_i32_e64 s[96:97], v158, v3
	v_max3_f32 v4, v4, v5, v6
	v_cndmask_b32_e64 v5, v146, v56, s[94:95]
	v_cndmask_b32_e64 v6, v146, v57, s[96:97]
	v_cmp_lt_i32_e64 s[90:91], v159, v3
	v_cmp_lt_i32_e64 s[92:93], v160, v3
	v_max3_f32 v4, v4, v5, v6
	v_cndmask_b32_e64 v5, v146, v58, s[90:91]
	v_cndmask_b32_e64 v6, v146, v59, s[92:93]
	v_cmp_lt_i32_e64 s[86:87], v161, v3
	v_cmp_lt_i32_e64 s[88:89], v162, v3
	v_max3_f32 v4, v4, v5, v6
	v_cndmask_b32_e64 v5, v146, v48, s[86:87]
	v_cndmask_b32_e64 v6, v146, v49, s[88:89]
	v_cmp_lt_i32_e64 s[82:83], v163, v3
	v_cmp_lt_i32_e64 s[84:85], v164, v3
	v_max3_f32 v4, v4, v5, v6
	v_cndmask_b32_e64 v5, v146, v50, s[82:83]
	v_cndmask_b32_e64 v6, v146, v51, s[84:85]
	v_cmp_lt_i32_e64 s[2:3], v165, v3
	v_cmp_lt_i32_e64 s[80:81], v166, v3
	v_cmp_lt_i32_e64 s[74:75], v167, v3
	v_max3_f32 v4, v4, v5, v6
	v_cndmask_b32_e64 v5, v146, v68, s[2:3]
	v_cndmask_b32_e64 v6, v146, v69, s[80:81]
	v_writelane_b32 v255, s74, 28
	v_max3_f32 v4, v4, v5, v6
	v_mov_b32_e32 v228, v1
	v_writelane_b32 v255, s75, 29
	v_cndmask_b32_e64 v5, v146, v70, s[74:75]
	v_cmp_lt_i32_e64 s[74:75], v168, v3
	v_mov_b32_e32 v226, v1
	v_mov_b32_e32 v223, v1
	v_writelane_b32 v255, s74, 30
	v_mov_b32_e32 v253, v1
	v_mov_b32_e32 v252, v1
	v_writelane_b32 v255, s75, 31
	v_cndmask_b32_e64 v6, v146, v71, s[74:75]
	v_cmp_lt_i32_e64 s[74:75], v169, v3
	v_max3_f32 v4, v4, v5, v6
	v_mov_b32_e32 v251, v1
	v_writelane_b32 v255, s74, 32
	v_mov_b32_e32 v250, v1
	v_mov_b32_e32 v233, v1
	v_writelane_b32 v255, s75, 33
	v_cndmask_b32_e64 v5, v146, v76, s[74:75]
	v_cmp_lt_i32_e64 s[74:75], v170, v3
	v_mov_b32_e32 v227, v1
	v_mov_b32_e32 v224, v1
	v_writelane_b32 v255, s74, 34
	v_mov_b32_e32 v202, v1
	s_nop 0
	v_writelane_b32 v255, s75, 35
	v_cndmask_b32_e64 v6, v146, v77, s[74:75]
	v_cmp_lt_i32_e64 s[74:75], v171, v3
	v_max3_f32 v4, v4, v5, v6
	s_nop 0
	v_writelane_b32 v255, s74, 36
	s_nop 1
	v_writelane_b32 v255, s75, 37
	v_cndmask_b32_e64 v5, v146, v78, s[74:75]
	v_cmp_lt_i32_e64 s[74:75], v172, v3
	s_nop 1
	v_writelane_b32 v255, s74, 38
	s_nop 1
	v_writelane_b32 v255, s75, 39
	v_cndmask_b32_e64 v6, v146, v79, s[74:75]
	v_cmp_lt_i32_e64 s[74:75], v173, v3
	v_max3_f32 v4, v4, v5, v6
	s_nop 0
	v_writelane_b32 v255, s74, 40
	s_nop 1
	v_writelane_b32 v255, s75, 41
	v_cndmask_b32_e64 v5, v146, v72, s[74:75]
	v_cmp_lt_i32_e64 s[74:75], v174, v3
	s_nop 1
	v_writelane_b32 v255, s74, 42
	s_nop 1
	v_writelane_b32 v255, s75, 43
	v_cndmask_b32_e64 v6, v146, v73, s[74:75]
	v_cmp_lt_i32_e64 s[74:75], v175, v3
	v_max3_f32 v4, v4, v5, v6
	s_nop 0
	v_writelane_b32 v255, s74, 44
	s_nop 1
	v_writelane_b32 v255, s75, 45
	v_cndmask_b32_e64 v5, v146, v74, s[74:75]
	v_cmp_lt_i32_e64 s[74:75], v176, v3
	s_nop 1
	v_writelane_b32 v255, s74, 46
	s_nop 1
	v_writelane_b32 v255, s75, 47
	v_cndmask_b32_e64 v6, v146, v75, s[74:75]
	v_cmp_lt_i32_e64 s[74:75], v177, v3
	v_max3_f32 v4, v4, v5, v6
	s_nop 0
	v_writelane_b32 v255, s74, 48
	s_nop 1
	v_writelane_b32 v255, s75, 49
	v_cndmask_b32_e64 v5, v146, v64, s[74:75]
	v_cmp_lt_i32_e64 s[74:75], v178, v3
	s_nop 1
	v_writelane_b32 v255, s74, 50
	s_nop 1
	v_writelane_b32 v255, s75, 51
	v_cndmask_b32_e64 v6, v146, v65, s[74:75]
	v_cmp_lt_i32_e64 s[74:75], v179, v3
	v_max3_f32 v4, v4, v5, v6
	s_nop 0
	v_writelane_b32 v255, s74, 52
	s_nop 1
	v_writelane_b32 v255, s75, 53
	v_cndmask_b32_e64 v5, v146, v66, s[74:75]
	v_cmp_lt_i32_e64 s[74:75], v180, v3
	s_nop 1
	v_writelane_b32 v255, s74, 54
	s_nop 1
	v_writelane_b32 v255, s75, 55
	v_cndmask_b32_e64 v6, v146, v67, s[74:75]
	v_cmp_lt_i32_e64 s[74:75], v181, v3
	v_max3_f32 v4, v4, v5, v6
	s_nop 0
	v_writelane_b32 v255, s74, 56
	s_nop 1
	v_writelane_b32 v255, s75, 57
	v_cndmask_b32_e64 v5, v146, v80, s[74:75]
	v_cmp_lt_i32_e64 s[74:75], v182, v3
	s_nop 1
	v_writelane_b32 v255, s74, 58
	s_nop 1
	v_writelane_b32 v255, s75, 59
	v_cndmask_b32_e64 v6, v146, v81, s[74:75]
	v_cmp_lt_i32_e64 s[74:75], v183, v3
	v_max3_f32 v4, v4, v5, v6
	s_nop 0
	v_writelane_b32 v255, s74, 60
	s_nop 1
	v_writelane_b32 v255, s75, 61
	v_cndmask_b32_e64 v5, v146, v82, s[74:75]
	v_cmp_lt_i32_e64 s[74:75], v184, v3
	s_nop 1
	v_cndmask_b32_e64 v3, v146, v83, s[74:75]
	v_max3_f32 v3, v4, v5, v3
	ds_bpermute_b32 v4, v106, v3
	s_waitcnt lgkmcnt(0)
	v_max_f32_e32 v4, v4, v4
	v_max_f32_e32 v3, v3, v4
	ds_bpermute_b32 v4, v107, v3
	s_waitcnt lgkmcnt(0)
	v_max_f32_e32 v4, v4, v4
	v_max_f32_e32 v3, v3, v4
	v_sub_f32_e32 v4, v24, v3
	v_exp_f32_e32 v4, v4
	v_sub_f32_e32 v5, v40, v3
	v_exp_f32_e32 v5, v5
	v_sub_f32_e32 v6, v41, v3
	v_cndmask_b32_e32 v229, 0, v4, vcc
	v_sub_f32_e32 v4, v25, v3
	v_exp_f32_e32 v4, v4
	v_exp_f32_e32 v6, v6
	v_cndmask_b32_e64 v213, 0, v5, s[36:37]
	v_sub_f32_e32 v5, v42, v3
	v_cndmask_b32_e64 v24, 0, v4, s[72:73]
	v_sub_f32_e32 v4, v26, v3
	v_exp_f32_e32 v4, v4
	v_exp_f32_e32 v5, v5
	v_cndmask_b32_e64 v230, 0, v4, s[70:71]
	v_sub_f32_e32 v4, v27, v3
	v_exp_f32_e32 v4, v4
	v_cndmask_b32_e64 v214, 0, v5, s[30:31]
	v_sub_f32_e32 v5, v32, v3
	v_exp_f32_e32 v5, v5
	v_cndmask_b32_e64 v25, 0, v4, s[68:69]
	v_sub_f32_e32 v4, v28, v3
	v_exp_f32_e32 v4, v4
	v_cndmask_b32_e64 v203, 0, v5, s[26:27]
	v_sub_f32_e32 v5, v34, v3
	v_exp_f32_e32 v5, v5
	v_cndmask_b32_e64 v231, 0, v4, s[66:67]
	v_sub_f32_e32 v4, v29, v3
	v_exp_f32_e32 v4, v4
	v_cndmask_b32_e64 v204, 0, v5, s[22:23]
	v_sub_f32_e32 v5, v44, v3
	v_exp_f32_e32 v5, v5
	v_cndmask_b32_e64 v26, 0, v4, s[64:65]
	v_sub_f32_e32 v4, v30, v3
	v_exp_f32_e32 v4, v4
	v_cndmask_b32_e64 v30, 0, v6, s[34:35]
	v_sub_f32_e32 v6, v43, v3
	v_exp_f32_e32 v6, v6
	v_cndmask_b32_e64 v232, 0, v4, s[62:63]
	v_sub_f32_e32 v4, v31, v3
	v_exp_f32_e32 v4, v4
	v_cndmask_b32_e64 v31, 0, v6, s[28:29]
	v_sub_f32_e32 v6, v33, v3
	v_exp_f32_e32 v6, v6
	v_cndmask_b32_e64 v27, 0, v4, s[60:61]
	v_sub_f32_e32 v4, v20, v3
	v_exp_f32_e32 v4, v4
	v_cndmask_b32_e64 v32, 0, v6, s[24:25]
	v_sub_f32_e32 v6, v35, v3
	v_exp_f32_e32 v6, v6
	v_cndmask_b32_e64 v215, 0, v4, s[58:59]
	v_sub_f32_e32 v4, v21, v3
	v_exp_f32_e32 v4, v4
	v_cndmask_b32_e64 v33, 0, v6, s[20:21]
	v_sub_f32_e32 v6, v45, v3
	v_exp_f32_e32 v6, v6
	v_cndmask_b32_e64 v20, 0, v4, s[56:57]
	v_sub_f32_e32 v4, v22, v3
	v_exp_f32_e32 v4, v4
	v_cndmask_b32_e64 v207, 0, v5, s[18:19]
	v_sub_f32_e32 v5, v46, v3
	v_exp_f32_e32 v5, v5
	v_cndmask_b32_e64 v216, 0, v4, s[54:55]
	v_sub_f32_e32 v4, v23, v3
	v_exp_f32_e32 v4, v4
	v_cndmask_b32_e64 v34, 0, v6, s[16:17]
	v_sub_f32_e32 v6, v47, v3
	v_exp_f32_e32 v6, v6
	v_cndmask_b32_e64 v21, 0, v4, s[52:53]
	v_sub_f32_e32 v4, v36, v3
	v_exp_f32_e32 v4, v4
	v_cndmask_b32_e64 v212, 0, v5, s[14:15]
	v_sub_f32_e32 v5, v60, v3
	v_exp_f32_e32 v5, v5
	v_cndmask_b32_e64 v217, 0, v4, s[50:51]
	v_sub_f32_e32 v4, v37, v3
	v_exp_f32_e32 v4, v4
	v_cndmask_b32_e64 v35, 0, v6, s[12:13]
	v_sub_f32_e32 v6, v61, v3
	v_exp_f32_e32 v6, v6
	v_cndmask_b32_e64 v22, 0, v4, s[48:49]
	v_sub_f32_e32 v4, v38, v3
	v_exp_f32_e32 v4, v4
	v_cndmask_b32_e64 v198, 0, v5, s[10:11]
	v_sub_f32_e32 v5, v62, v3
	v_exp_f32_e32 v5, v5
	v_cndmask_b32_e64 v218, 0, v4, s[46:47]
	v_sub_f32_e32 v4, v39, v3
	v_exp_f32_e32 v4, v4
	v_cndmask_b32_e64 v36, 0, v6, s[8:9]
	v_sub_f32_e32 v6, v63, v3
	v_exp_f32_e32 v6, v6
	v_cndmask_b32_e64 v23, 0, v4, s[44:45]
	v_sub_f32_e32 v4, v52, v3
	v_exp_f32_e32 v4, v4
	v_cndmask_b32_e64 v199, 0, v5, s[6:7]
	v_sub_f32_e32 v5, v56, v3
	v_exp_f32_e32 v5, v5
	v_cndmask_b32_e64 v205, 0, v4, s[42:43]
	v_sub_f32_e32 v4, v53, v3
	v_exp_f32_e32 v4, v4
	v_cndmask_b32_e64 v44, 0, v6, s[4:5]
	v_sub_f32_e32 v6, v57, v3
	v_exp_f32_e32 v6, v6
	v_cndmask_b32_e64 v28, 0, v4, s[40:41]
	v_sub_f32_e32 v4, v54, v3
	v_exp_f32_e32 v4, v4
	v_cndmask_b32_e64 v200, 0, v5, s[94:95]
	v_sub_f32_e32 v5, v58, v3
	v_exp_f32_e32 v5, v5
	v_cndmask_b32_e64 v206, 0, v4, s[0:1]
	v_sub_f32_e32 v4, v55, v3
	v_exp_f32_e32 v4, v4
	v_cndmask_b32_e64 v37, 0, v6, s[96:97]
	v_sub_f32_e32 v6, v59, v3
	v_exp_f32_e32 v6, v6
	v_cndmask_b32_e64 v29, 0, v4, s[38:39]
	v_add_f32_e32 v4, 0, v229
	v_add_f32_e32 v4, v24, v4
	v_cndmask_b32_e64 v201, 0, v5, s[90:91]
	v_sub_f32_e32 v5, v48, v3
	v_add_f32_e32 v4, v230, v4
	v_exp_f32_e32 v5, v5
	v_add_f32_e32 v4, v25, v4
	v_add_f32_e32 v4, v231, v4
	v_cndmask_b32_e64 v47, 0, v6, s[92:93]
	v_sub_f32_e32 v6, v49, v3
	v_add_f32_e32 v4, v26, v4
	v_exp_f32_e32 v6, v6
	v_add_f32_e32 v4, v232, v4
	v_cndmask_b32_e64 v192, 0, v5, s[86:87]
	v_sub_f32_e32 v5, v50, v3
	v_add_f32_e32 v4, v27, v4
	v_exp_f32_e32 v5, v5
	v_add_f32_e32 v4, v215, v4
	v_add_f32_e32 v4, v20, v4
	v_cndmask_b32_e64 v38, 0, v6, s[88:89]
	v_sub_f32_e32 v6, v51, v3
	v_add_f32_e32 v4, v216, v4
	v_exp_f32_e32 v6, v6
	v_add_f32_e32 v4, v21, v4
	v_cndmask_b32_e64 v193, 0, v5, s[82:83]
	v_sub_f32_e32 v5, v68, v3
	v_add_f32_e32 v4, v217, v4
	v_exp_f32_e32 v5, v5
	v_add_f32_e32 v4, v22, v4
	v_add_f32_e32 v4, v218, v4
	v_cndmask_b32_e64 v50, 0, v6, s[84:85]
	v_sub_f32_e32 v6, v69, v3
	v_add_f32_e32 v4, v23, v4
	v_exp_f32_e32 v6, v6
	v_add_f32_e32 v4, v205, v4
	v_cndmask_b32_e64 v194, 0, v5, s[2:3]
	v_sub_f32_e32 v5, v70, v3
	v_add_f32_e32 v4, v28, v4
	v_exp_f32_e32 v5, v5
	v_add_f32_e32 v4, v206, v4
	v_add_f32_e32 v4, v29, v4
	v_cndmask_b32_e64 v39, 0, v6, s[80:81]
	v_sub_f32_e32 v6, v71, v3
	v_readlane_b32 s2, v255, 28
	v_add_f32_e32 v4, v213, v4
	v_exp_f32_e32 v6, v6
	v_readlane_b32 s3, v255, 29
	v_add_f32_e32 v4, v30, v4
	v_add_f32_e32 v4, v214, v4
	v_cndmask_b32_e64 v195, 0, v5, s[2:3]
	v_sub_f32_e32 v5, v76, v3
	v_readlane_b32 s2, v255, 30
	v_exp_f32_e32 v5, v5
	v_add_f32_e32 v4, v31, v4
	v_readlane_b32 s3, v255, 31
	v_add_f32_e32 v4, v203, v4
	v_add_f32_e32 v4, v32, v4
	v_cndmask_b32_e64 v52, 0, v6, s[2:3]
	v_sub_f32_e32 v6, v77, v3
	v_readlane_b32 s2, v255, 32
	v_exp_f32_e32 v6, v6
	v_readlane_b32 s3, v255, 33
	v_add_f32_e32 v4, v204, v4
	v_add_f32_e32 v4, v33, v4
	v_cndmask_b32_e64 v76, 0, v5, s[2:3]
	v_sub_f32_e32 v5, v78, v3
	v_readlane_b32 s2, v255, 34
	v_exp_f32_e32 v5, v5
	v_add_f32_e32 v4, v207, v4
	v_readlane_b32 s3, v255, 35
	v_add_f32_e32 v4, v34, v4
	v_add_f32_e32 v4, v212, v4
	v_cndmask_b32_e64 v40, 0, v6, s[2:3]
	v_sub_f32_e32 v6, v79, v3
	v_readlane_b32 s2, v255, 36
	v_exp_f32_e32 v6, v6
	v_readlane_b32 s3, v255, 37
	v_add_f32_e32 v4, v35, v4
	v_add_f32_e32 v4, v198, v4
	v_cndmask_b32_e64 v77, 0, v5, s[2:3]
	v_sub_f32_e32 v5, v72, v3
	v_readlane_b32 s2, v255, 38
	v_exp_f32_e32 v5, v5
	v_add_f32_e32 v4, v36, v4
	v_readlane_b32 s3, v255, 39
	v_add_f32_e32 v4, v199, v4
	v_add_f32_e32 v4, v44, v4
	v_cndmask_b32_e64 v58, 0, v6, s[2:3]
	v_sub_f32_e32 v6, v73, v3
	v_readlane_b32 s2, v255, 40
	v_exp_f32_e32 v6, v6
	v_readlane_b32 s3, v255, 41
	v_add_f32_e32 v4, v200, v4
	v_add_f32_e32 v4, v37, v4
	v_cndmask_b32_e64 v78, 0, v5, s[2:3]
	v_sub_f32_e32 v5, v74, v3
	v_readlane_b32 s2, v255, 42
	v_exp_f32_e32 v5, v5
	v_add_f32_e32 v4, v201, v4
	v_readlane_b32 s3, v255, 43
	v_add_f32_e32 v4, v47, v4
	v_add_f32_e32 v4, v192, v4
	v_cndmask_b32_e64 v41, 0, v6, s[2:3]
	v_sub_f32_e32 v6, v75, v3
	v_readlane_b32 s2, v255, 44
	v_exp_f32_e32 v6, v6
	v_readlane_b32 s3, v255, 45
	v_add_f32_e32 v4, v38, v4
	v_add_f32_e32 v4, v193, v4
	v_cndmask_b32_e64 v191, 0, v5, s[2:3]
	v_sub_f32_e32 v5, v64, v3
	v_readlane_b32 s2, v255, 46
	v_exp_f32_e32 v5, v5
	v_add_f32_e32 v4, v50, v4
	v_readlane_b32 s3, v255, 47
	v_add_f32_e32 v4, v194, v4
	v_add_f32_e32 v4, v39, v4
	v_cndmask_b32_e64 v60, 0, v6, s[2:3]
	v_sub_f32_e32 v6, v65, v3
	v_readlane_b32 s2, v255, 48
	v_exp_f32_e32 v6, v6
	v_readlane_b32 s3, v255, 49
	v_add_f32_e32 v4, v195, v4
	v_add_f32_e32 v4, v52, v4
	v_cndmask_b32_e64 v70, 0, v5, s[2:3]
	v_sub_f32_e32 v5, v66, v3
	v_readlane_b32 s2, v255, 50
	v_exp_f32_e32 v5, v5
	v_add_f32_e32 v4, v76, v4
	v_readlane_b32 s3, v255, 51
	v_add_f32_e32 v4, v40, v4
	v_add_f32_e32 v4, v77, v4
	v_cndmask_b32_e64 v42, 0, v6, s[2:3]
	v_sub_f32_e32 v6, v67, v3
	v_readlane_b32 s2, v255, 52
	v_exp_f32_e32 v6, v6
	v_readlane_b32 s3, v255, 53
	v_add_f32_e32 v4, v58, v4
	v_add_f32_e32 v4, v78, v4
	v_cndmask_b32_e64 v71, 0, v5, s[2:3]
	v_sub_f32_e32 v5, v80, v3
	v_readlane_b32 s2, v255, 54
	v_exp_f32_e32 v5, v5
	v_add_f32_e32 v4, v41, v4
	v_readlane_b32 s3, v255, 55
	v_add_f32_e32 v4, v191, v4
	v_add_f32_e32 v4, v60, v4
	v_cndmask_b32_e64 v148, 0, v6, s[2:3]
	v_sub_f32_e32 v6, v81, v3
	v_readlane_b32 s2, v255, 56
	v_exp_f32_e32 v6, v6
	v_readlane_b32 s3, v255, 57
	v_add_f32_e32 v4, v70, v4
	v_add_f32_e32 v4, v42, v4
	v_cndmask_b32_e64 v72, 0, v5, s[2:3]
	v_sub_f32_e32 v5, v82, v3
	v_readlane_b32 s2, v255, 58
	v_exp_f32_e32 v5, v5
	v_sub_f32_e32 v3, v83, v3
	v_add_f32_e32 v4, v71, v4
	v_readlane_b32 s3, v255, 59
	v_exp_f32_e32 v3, v3
	v_add_f32_e32 v4, v148, v4
	v_cndmask_b32_e64 v43, 0, v6, s[2:3]
	v_readlane_b32 s2, v255, 60
	v_add_f32_e32 v4, v72, v4
	v_readlane_b32 s3, v255, 61
	v_add_f32_e32 v4, v43, v4
	v_cndmask_b32_e64 v225, 0, v3, s[74:75]
	v_cndmask_b32_e64 v73, 0, v5, s[2:3]
	v_add_f32_e32 v4, v73, v4
	v_add_f32_e32 v3, v225, v4
	ds_bpermute_b32 v4, v106, v3
	s_add_i32 s40, s76, 1
	s_cmp_lg_u32 s76, 7
	s_cselect_b32 s0, s40, 7
	s_cmp_lt_u32 s0, 4
	v_readlane_b32 s15, v255, 26
	v_readlane_b32 s20, v255, 27
	s_cselect_b32 s1, s20, s15
	s_waitcnt lgkmcnt(0)
	v_add_f32_e32 v3, v3, v4
	s_lshl_b32 s0, s0, 2
	v_add_u32_e32 v5, s1, v189
	ds_bpermute_b32 v6, v107, v3
	v_and_or_b32 v4, s0, 12, v5
	v_ashrrev_i32_e32 v5, 31, v4
	v_lshlrev_b64 v[4:5], 12, v[4:5]
	v_lshl_add_u64 v[4:5], v[94:95], 0, v[4:5]
	s_waitcnt lgkmcnt(0)
	v_add_f32_e32 v3, v3, v6
	global_load_dwordx4 v[16:19], v[4:5], off
	global_load_dwordx4 v[12:15], v[4:5], off offset:64
	global_load_dwordx4 v[8:11], v[4:5], off offset:128
	s_nop 0
	global_load_dwordx4 v[4:7], v[4:5], off offset:192
	v_div_scale_f32 v45, s[0:1], v3, v3, 1.0
	v_rcp_f32_e32 v46, v45
	v_mov_b32_e32 v59, v1
	v_readlane_b32 s16, v255, 18
	v_readlane_b32 s17, v255, 19
	v_fma_f32 v48, -v45, v46, 1.0
	v_fmac_f32_e32 v46, v48, v46
	v_div_scale_f32 v48, vcc, 1.0, v3, 1.0
	v_mul_f32_e32 v49, v48, v46
	v_fma_f32 v51, -v45, v49, v48
	v_fmac_f32_e32 v49, v51, v46
	v_fma_f32 v45, -v45, v49, v48
	v_div_fmas_f32 v45, v45, v46, v49
	v_div_fixup_f32 v45, v45, v3, 1.0
	v_cmp_lt_f32_e32 vcc, 0, v3
	v_mov_b32_e32 v61, v1
	v_mov_b32_e32 v57, v1
	v_cndmask_b32_e32 v74, 0, v45, vcc
	v_mul_f32_e32 v246, v24, v74
	v_fma_f32 v3, v229, v74, v246
	v_mul_f32_e32 v247, v25, v74
	v_fmac_f32_e32 v3, v230, v74
	v_fma_f32 v3, 2.0, v3, v247
	v_mul_f32_e32 v248, v26, v74
	v_mul_f32_e32 v249, v27, v74
	v_add_f32_dpp v53, v3, v3 quad_perm:[1,0,3,2] row_mask:0xf bank_mask:0xf bound_ctrl:1
	v_mov_b32_e32 v3, v1
	v_mul_f32_e32 v242, v20, v74
	v_mul_f32_e32 v243, v21, v74
	v_mov_b32_dpp v3, v247 quad_perm:[1,0,3,2] row_mask:0xf bank_mask:0xf
	v_fmac_f32_e32 v3, v25, v74
	v_mul_f32_e32 v244, v22, v74
	v_mul_f32_e32 v245, v23, v74
	v_add_f32_dpp v56, v3, v3 quad_perm:[2,3,0,1] row_mask:0xf bank_mask:0xf bound_ctrl:1
	v_fma_f32 v3, v231, v74, v248
	v_fmac_f32_e32 v3, v232, v74
	v_fma_f32 v3, 2.0, v3, v249
	v_mul_f32_e32 v238, v28, v74
	v_mul_f32_e32 v75, v42, v74
	v_add_f32_dpp v48, v3, v3 quad_perm:[1,0,3,2] row_mask:0xf bank_mask:0xf bound_ctrl:1
	v_fma_f32 v3, v215, v74, v242
	v_fmac_f32_e32 v3, v216, v74
	v_fma_f32 v3, 2.0, v3, v243
	v_mul_f32_e32 v239, v29, v74
	v_mul_f32_e32 v240, v30, v74
	v_add_f32_dpp v45, v3, v3 quad_perm:[1,0,3,2] row_mask:0xf bank_mask:0xf bound_ctrl:1
	v_fma_f32 v3, v217, v74, v244
	v_fmac_f32_e32 v3, v218, v74
	v_fma_f32 v3, 2.0, v3, v245
	v_mul_f32_e32 v82, v40, v74
	v_mul_f32_e32 v241, v31, v74
	v_add_f32_dpp v42, v3, v3 quad_perm:[1,0,3,2] row_mask:0xf bank_mask:0xf bound_ctrl:1
	v_fma_f32 v3, v205, v74, v238
	v_fmac_f32_e32 v3, v206, v74
	v_fma_f32 v3, 2.0, v3, v239
	v_mul_f32_e32 v234, v32, v74
	v_mul_f32_e32 v208, v38, v74
	v_add_f32_dpp v40, v3, v3 quad_perm:[1,0,3,2] row_mask:0xf bank_mask:0xf bound_ctrl:1
	v_fma_f32 v3, v213, v74, v240
	v_fmac_f32_e32 v3, v214, v74
	v_fma_f32 v3, 2.0, v3, v241
	v_mul_f32_e32 v235, v33, v74
	v_mul_f32_e32 v236, v34, v74
	v_add_f32_dpp v38, v3, v3 quad_perm:[1,0,3,2] row_mask:0xf bank_mask:0xf bound_ctrl:1
	v_fma_f32 v3, v203, v74, v234
	v_fmac_f32_e32 v3, v204, v74
	v_fma_f32 v3, 2.0, v3, v235
	v_mul_f32_e32 v219, v36, v74
	v_mul_f32_e32 v237, v35, v74
	v_add_f32_dpp v36, v3, v3 quad_perm:[1,0,3,2] row_mask:0xf bank_mask:0xf bound_ctrl:1
	v_fma_f32 v3, v207, v74, v236
	v_fmac_f32_e32 v3, v212, v74
	v_fma_f32 v3, 2.0, v3, v237
	v_mul_f32_e32 v220, v44, v74
	v_mul_f32_e32 v221, v37, v74
	v_add_f32_dpp v34, v3, v3 quad_perm:[1,0,3,2] row_mask:0xf bank_mask:0xf bound_ctrl:1
	v_fma_f32 v3, v198, v74, v219
	v_fmac_f32_e32 v3, v199, v74
	v_fma_f32 v3, 2.0, v3, v220
	v_mul_f32_e32 v222, v47, v74
	v_mul_f32_e32 v209, v50, v74
	v_add_f32_dpp v32, v3, v3 quad_perm:[1,0,3,2] row_mask:0xf bank_mask:0xf bound_ctrl:1
	v_fma_f32 v3, v200, v74, v221
	v_fmac_f32_e32 v3, v201, v74
	v_fma_f32 v3, 2.0, v3, v222
	v_mul_f32_e32 v210, v39, v74
	v_mul_f32_e32 v211, v52, v74
	v_add_f32_dpp v30, v3, v3 quad_perm:[1,0,3,2] row_mask:0xf bank_mask:0xf bound_ctrl:1
	v_fma_f32 v3, v192, v74, v208
	v_fmac_f32_e32 v3, v193, v74
	v_fma_f32 v3, 2.0, v3, v209
	v_mul_f32_e32 v83, v58, v74
	v_mul_f32_e32 v196, v41, v74
	v_add_f32_dpp v28, v3, v3 quad_perm:[1,0,3,2] row_mask:0xf bank_mask:0xf bound_ctrl:1
	v_fma_f32 v3, v194, v74, v210
	v_fmac_f32_e32 v3, v195, v74
	v_fma_f32 v3, 2.0, v3, v211
	v_mul_f32_e32 v197, v60, v74
	v_mov_b32_dpp v59, v222 quad_perm:[1,0,3,2] row_mask:0xf bank_mask:0xf
	v_add_f32_dpp v26, v3, v3 quad_perm:[1,0,3,2] row_mask:0xf bank_mask:0xf bound_ctrl:1
	v_fma_f32 v3, v76, v74, v82
	v_fmac_f32_e32 v3, v77, v74
	v_fma_f32 v3, 2.0, v3, v83
	v_mul_f32_e32 v79, v148, v74
	v_fmac_f32_e32 v59, v47, v74
	v_add_f32_dpp v24, v3, v3 quad_perm:[1,0,3,2] row_mask:0xf bank_mask:0xf bound_ctrl:1
	v_fma_f32 v3, v78, v74, v196
	v_fmac_f32_e32 v3, v191, v74
	v_fma_f32 v3, 2.0, v3, v197
	v_mov_b32_e32 v47, v1
	v_mul_f32_e32 v80, v43, v74
	v_add_f32_dpp v22, v3, v3 quad_perm:[1,0,3,2] row_mask:0xf bank_mask:0xf bound_ctrl:1
	v_fma_f32 v3, v70, v74, v75
	v_fmac_f32_e32 v3, v71, v74
	v_mov_b32_dpp v47, v79 quad_perm:[1,0,3,2] row_mask:0xf bank_mask:0xf
	v_mov_b32_e32 v54, v1
	v_fma_f32 v3, 2.0, v3, v79
	v_fmac_f32_e32 v47, v148, v74
	v_cndmask_b32_e64 v148, v56, 0, s[16:17]
	v_mov_b32_dpp v61, v220 quad_perm:[1,0,3,2] row_mask:0xf bank_mask:0xf
	v_mov_b32_dpp v57, v209 quad_perm:[1,0,3,2] row_mask:0xf bank_mask:0xf
	v_mov_b32_dpp v54, v211 quad_perm:[1,0,3,2] row_mask:0xf bank_mask:0xf
	v_add_f32_dpp v20, v3, v3 quad_perm:[1,0,3,2] row_mask:0xf bank_mask:0xf bound_ctrl:1
	v_fma_f32 v3, v72, v74, v80
	ds_bpermute_b32 v148, v108, v148
	v_mul_f32_e32 v81, v225, v74
	v_mov_b32_e32 v69, v1
	v_mov_b32_e32 v67, v1
	v_mov_b32_e32 v65, v1
	v_mov_b32_e32 v63, v1
	v_fmac_f32_e32 v61, v44, v74
	v_fmac_f32_e32 v57, v50, v74
	v_fmac_f32_e32 v54, v52, v74
	v_mov_b32_e32 v52, v1
	v_mov_b32_e32 v50, v1
	v_fmac_f32_e32 v3, v73, v74
	v_mov_b32_e32 v44, v1
	v_mov_b32_dpp v228, v249 quad_perm:[1,0,3,2] row_mask:0xf bank_mask:0xf
	v_mov_b32_dpp v226, v243 quad_perm:[1,0,3,2] row_mask:0xf bank_mask:0xf
	v_mov_b32_dpp v223, v245 quad_perm:[1,0,3,2] row_mask:0xf bank_mask:0xf
	v_mov_b32_dpp v69, v239 quad_perm:[1,0,3,2] row_mask:0xf bank_mask:0xf
	v_mov_b32_dpp v67, v241 quad_perm:[1,0,3,2] row_mask:0xf bank_mask:0xf
	v_mov_b32_dpp v65, v235 quad_perm:[1,0,3,2] row_mask:0xf bank_mask:0xf
	v_mov_b32_dpp v63, v237 quad_perm:[1,0,3,2] row_mask:0xf bank_mask:0xf
	v_mov_b32_dpp v52, v83 quad_perm:[1,0,3,2] row_mask:0xf bank_mask:0xf
	v_mov_b32_dpp v50, v197 quad_perm:[1,0,3,2] row_mask:0xf bank_mask:0xf
	v_fma_f32 v3, 2.0, v3, v81
	v_mov_b32_dpp v44, v81 quad_perm:[1,0,3,2] row_mask:0xf bank_mask:0xf
	v_mov_b32_e32 v55, v1
	v_mov_b32_e32 v51, v1
	v_fmac_f32_e32 v228, v27, v74
	v_mov_b32_e32 v49, v1
	v_fmac_f32_e32 v226, v21, v74
	v_mov_b32_e32 v46, v1
	v_fmac_f32_e32 v223, v23, v74
	v_mov_b32_e32 v43, v1
	v_fmac_f32_e32 v69, v29, v74
	v_mov_b32_e32 v41, v1
	v_fmac_f32_e32 v67, v31, v74
	v_mov_b32_e32 v39, v1
	v_fmac_f32_e32 v65, v33, v74
	v_mov_b32_e32 v37, v1
	v_fmac_f32_e32 v63, v35, v74
	v_mov_b32_e32 v35, v1
	v_mov_b32_e32 v33, v1
	v_mov_b32_e32 v68, v1
	v_mov_b32_e32 v31, v1
	v_mov_b32_e32 v66, v1
	v_mov_b32_e32 v29, v1
	v_mov_b32_e32 v64, v1
	v_mov_b32_e32 v27, v1
	v_fmac_f32_e32 v52, v58, v74
	v_mov_b32_e32 v62, v1
	v_mov_b32_e32 v25, v1
	v_fmac_f32_e32 v50, v60, v74
	v_mov_b32_e32 v60, v1
	v_mov_b32_e32 v23, v1
	v_mov_b32_e32 v58, v1
	v_add_f32_dpp v3, v3, v3 quad_perm:[1,0,3,2] row_mask:0xf bank_mask:0xf bound_ctrl:1
	v_mov_b32_e32 v21, v1
	v_fmac_f32_e32 v44, v225, v74
	v_mov_b32_e32 v225, v1
	v_readlane_b32 s18, v255, 20
	v_mov_b32_dpp v55, v53 quad_perm:[2,3,0,1] row_mask:0xf bank_mask:0xf
	v_mov_b32_dpp v51, v48 quad_perm:[2,3,0,1] row_mask:0xf bank_mask:0xf
	v_mov_b32_dpp v253, v228 quad_perm:[2,3,0,1] row_mask:0xf bank_mask:0xf
	v_mov_b32_dpp v49, v45 quad_perm:[2,3,0,1] row_mask:0xf bank_mask:0xf
	v_mov_b32_dpp v252, v226 quad_perm:[2,3,0,1] row_mask:0xf bank_mask:0xf
	v_mov_b32_dpp v46, v42 quad_perm:[2,3,0,1] row_mask:0xf bank_mask:0xf
	v_mov_b32_dpp v251, v223 quad_perm:[2,3,0,1] row_mask:0xf bank_mask:0xf
	v_mov_b32_dpp v43, v40 quad_perm:[2,3,0,1] row_mask:0xf bank_mask:0xf
	v_mov_b32_dpp v250, v69 quad_perm:[2,3,0,1] row_mask:0xf bank_mask:0xf
	v_mov_b32_dpp v41, v38 quad_perm:[2,3,0,1] row_mask:0xf bank_mask:0xf
	v_mov_b32_dpp v233, v67 quad_perm:[2,3,0,1] row_mask:0xf bank_mask:0xf
	v_mov_b32_dpp v39, v36 quad_perm:[2,3,0,1] row_mask:0xf bank_mask:0xf
	v_mov_b32_dpp v227, v65 quad_perm:[2,3,0,1] row_mask:0xf bank_mask:0xf
	v_mov_b32_dpp v37, v34 quad_perm:[2,3,0,1] row_mask:0xf bank_mask:0xf
	v_mov_b32_dpp v224, v63 quad_perm:[2,3,0,1] row_mask:0xf bank_mask:0xf
	v_mov_b32_dpp v35, v32 quad_perm:[2,3,0,1] row_mask:0xf bank_mask:0xf
	v_mov_b32_dpp v202, v61 quad_perm:[2,3,0,1] row_mask:0xf bank_mask:0xf
	v_mov_b32_dpp v33, v30 quad_perm:[2,3,0,1] row_mask:0xf bank_mask:0xf
	v_mov_b32_dpp v68, v59 quad_perm:[2,3,0,1] row_mask:0xf bank_mask:0xf
	v_mov_b32_dpp v31, v28 quad_perm:[2,3,0,1] row_mask:0xf bank_mask:0xf
	v_mov_b32_dpp v66, v57 quad_perm:[2,3,0,1] row_mask:0xf bank_mask:0xf
	v_mov_b32_dpp v29, v26 quad_perm:[2,3,0,1] row_mask:0xf bank_mask:0xf
	v_mov_b32_dpp v64, v54 quad_perm:[2,3,0,1] row_mask:0xf bank_mask:0xf
	v_mov_b32_dpp v27, v24 quad_perm:[2,3,0,1] row_mask:0xf bank_mask:0xf
	v_mov_b32_dpp v62, v52 quad_perm:[2,3,0,1] row_mask:0xf bank_mask:0xf
	v_mov_b32_dpp v25, v22 quad_perm:[2,3,0,1] row_mask:0xf bank_mask:0xf
	v_mov_b32_dpp v60, v50 quad_perm:[2,3,0,1] row_mask:0xf bank_mask:0xf
	v_mov_b32_dpp v23, v20 quad_perm:[2,3,0,1] row_mask:0xf bank_mask:0xf
	v_mov_b32_dpp v58, v47 quad_perm:[2,3,0,1] row_mask:0xf bank_mask:0xf
	v_mov_b32_dpp v21, v3 quad_perm:[2,3,0,1] row_mask:0xf bank_mask:0xf
	v_mov_b32_dpp v225, v44 quad_perm:[2,3,0,1] row_mask:0xf bank_mask:0xf
	v_readlane_b32 s19, v255, 21
	s_and_saveexec_b64 s[0:1], s[18:19]
	s_cbranch_execz .LBB0_416
	v_add_f32_e32 v53, v53, v55
	s_waitcnt lgkmcnt(0)
	v_add_f32_e32 v53, v53, v148
	ds_write_b32 v188, v53

.LBB0_728:
	s_or_b64 exec, exec, s[14:15]
	s_load_dword s14, s[64:65], 0x10
	v_lshlrev_b32_e32 v0, 3, v10
	v_and_b32_e32 v0, 56, v0
	v_ashrrev_i32_e32 v23, 3, v11
	v_cmp_gt_u32_e64 s[0:1], 48, v18
	s_waitcnt lgkmcnt(0)
	s_lshr_b32 s14, s14, 16
	s_cmp_lg_u32 s14, 0
	s_cselect_b64 s[14:15], -1, 0
	s_cmp_lg_u64 s[14:15], 0
	s_movk_i32 s14, 0x104
	s_addc_u32 s43, s66, 0
	v_mul_lo_u32 v24, v22, s14
	s_lshl_b32 s14, s39, 6
	v_mul_u32_u24_e32 v25, 0x104, v0
	s_sub_i32 s44, 0, s14
	s_lshl_b32 s45, s42, 6
	s_lshl_b32 s46, s43, 6
	s_mov_b64 s[14:15], 0
	v_lshlrev_b32_e32 v20, 2, v18
	v_lshlrev_b32_e32 v0, 1, v0
	s_waitcnt vmcnt(0)
	s_branch .LBB0_730
.LBB0_729:
	s_or_b64 exec, exec, s[22:23]
	s_and_b64 s[20:21], s[14:15], exec
	s_cselect_b32 s20, 0x4100, 0
	s_abs_i32 s22, s42
	s_add_i32 s20, s20, 16
	v_lshlrev_b32_e32 v21, 2, v18
	s_mul_hi_u32 s23, s22, s41
	v_add3_u32 v21, s20, v24, v21
	s_mul_i32 s24, s23, s39
	ds_write2_b32 v21, v6, v7 offset1:1
	ds_write2_b32 v21, v8, v9 offset0:2 offset1:3
	v_add_u32_e32 v6, 0x2080, v21
	s_sub_i32 s22, s22, s24
	ds_write2_b32 v6, v2, v3 offset1:1
	v_add_u32_e32 v2, 0x2088, v21
	s_ashr_i32 s21, s42, 31
	s_add_i32 s24, s23, 1
	s_sub_i32 s25, s22, s39
	ds_write2_b32 v2, v4, v5 offset1:1
	s_cmp_ge_u32 s22, s39
	v_lshlrev_b32_e32 v2, 2, v23
	s_cselect_b32 s23, s24, s23
	v_add3_u32 v6, s20, v25, v2
	s_waitcnt lgkmcnt(0)
	s_barrier
	s_cselect_b32 s22, s25, s22
	s_add_i32 s24, s23, 1
	ds_read2_b32 v[2:3], v6 offset1:65
	ds_read2_b32 v[4:5], v6 offset0:130 offset1:195
	v_add_u32_e32 v8, 0x400, v6
	s_cmp_ge_u32 s22, s39
	ds_read2_b32 v[6:7], v8 offset0:4 offset1:69
	ds_read2_b32 v[8:9], v8 offset0:134 offset1:199
	s_cselect_b32 s22, s24, s23
	s_xor_b32 s22, s22, s21
	s_sub_i32 s21, s22, s21
	s_mul_i32 s22, s44, s21
	s_waitcnt lgkmcnt(3)
	v_cvt_pk_bf16_f32 v2, v2, v3
	s_waitcnt lgkmcnt(2)
	v_cvt_pk_bf16_f32 v3, v4, v5
	s_waitcnt lgkmcnt(1)
	v_cvt_pk_bf16_f32 v4, v6, v7
	v_lshl_add_u32 v6, s21, 6, v23
	s_add_i32 s20, s45, s22
	s_waitcnt lgkmcnt(0)
	v_cvt_pk_bf16_f32 v5, v8, v9
	v_ashrrev_i32_e32 v9, 31, v6
	v_mad_u64_u32 v[6:7], s[22:23], v6, s38, 0
	v_mov_b32_e32 v8, v7
	v_mad_u64_u32 v[8:9], s[22:23], v9, s38, v[8:9]
	v_mov_b32_e32 v7, v8
	s_ashr_i32 s21, s20, 31
	v_lshl_add_u64 v[6:7], v[6:7], 1, s[10:11]
	v_lshl_add_u64 v[6:7], s[20:21], 1, v[6:7]
	v_lshl_add_u64 v[6:7], v[6:7], 0, v[0:1]
	global_store_dwordx4 v[6:7], v[2:5], off
	s_xor_b64 s[14:15], s[14:15], -1
	s_add_i32 s45, s45, s46
	s_andn2_b64 vcc, exec, s[18:19]
	s_mov_b32 s42, s47
	s_waitcnt vmcnt(1)
	v_mov_b32_e32 v6, v14
	v_mov_b32_e32 v7, v15
	v_mov_b32_e32 v8, v16
	v_mov_b32_e32 v9, v17
	v_mov_b32_e32 v2, v10
	v_mov_b32_e32 v3, v11
	v_mov_b32_e32 v4, v12
	v_mov_b32_e32 v5, v13
	s_cbranch_vccz .LBB0_694
